# v38 + in the five main GEMM K-loops each load segment issues its LDS-DMA loads before its ds_read fragment reads (memory requests go out ~16 LDS reads earlier; dependency-checked reorder, one s_nop ad
# baseline (speedup 1.0000x reference)
.LBB0_364:
	s_add_u32 s20, s18, 0xfff80080
	s_addc_u32 s21, s19, -1
	s_add_i32 s30, 0, 0x10000
	s_cmp_eq_u32 s29, 28
	s_cselect_b32 s23, s4, s21
	s_cselect_b32 s22, s24, s20
	s_cselect_b32 s21, s25, s28
	s_cselect_b32 s20, s26, s27
	s_add_i32 s42, 0, 0x14000
	v_lshl_add_u64 v[202:203], s[18:19], 0, v[162:163]
	s_add_i32 m0, s87, 0xc000
	s_nop 0
	global_load_lds_dwordx4 v[202:203], off
	v_lshl_add_u64 v[202:203], s[18:19], 0, v[164:165]
	s_add_i32 m0, s87, 0xe000
	s_nop 0
	global_load_lds_dwordx4 v[202:203], off
	v_add_u32_e32 v142, s30, v204
	v_add_u32_e32 v166, s42, v204
	ds_read_b128 v[130:133], v142
	ds_read_b128 v[134:137], v142 offset:1024
	ds_read_b128 v[138:141], v142 offset:2048
	ds_read_b128 v[142:145], v142 offset:3072
	ds_read_b128 v[146:149], v166
	ds_read_b128 v[150:153], v166 offset:1024
	ds_read_b128 v[154:157], v166 offset:2048
	ds_read_b128 v[166:169], v166 offset:3072
	ds_read_b128 v[170:173], v205
	ds_read_b128 v[174:177], v205 offset:1024
	ds_read_b128 v[178:181], v205 offset:2048
	ds_read_b128 v[182:185], v205 offset:3072
	ds_read_b128 v[186:189], v205 offset:4096
	ds_read_b128 v[190:193], v205 offset:5120
	ds_read_b128 v[206:209], v205 offset:6144
	ds_read_b128 v[210:213], v205 offset:7168


	s_waitcnt vmcnt(8)
	s_waitcnt lgkmcnt(0)
	s_setprio 1
	s_barrier
	v_mfma_f32_16x16x32_bf16 v[126:129], v[130:133], v[170:173], v[126:129]
	v_mfma_f32_16x16x32_bf16 v[126:129], v[134:137], v[174:177], v[126:129]
	v_mfma_f32_16x16x32_bf16 v[110:113], v[134:137], v[182:185], v[110:113]
	v_mfma_f32_16x16x32_bf16 v[110:113], v[130:133], v[178:181], v[110:113]
	v_mfma_f32_16x16x32_bf16 v[94:97], v[130:133], v[186:189], v[94:97]
	v_mfma_f32_16x16x32_bf16 v[94:97], v[134:137], v[190:193], v[94:97]
	v_mfma_f32_16x16x32_bf16 v[78:81], v[134:137], v[210:213], v[78:81]
	v_mfma_f32_16x16x32_bf16 v[78:81], v[130:133], v[206:209], v[78:81]
	v_mfma_f32_16x16x32_bf16 v[74:77], v[138:141], v[206:209], v[74:77]
	v_mfma_f32_16x16x32_bf16 v[74:77], v[142:145], v[210:213], v[74:77]
	v_mfma_f32_16x16x32_bf16 v[90:93], v[142:145], v[190:193], v[90:93]
	v_mfma_f32_16x16x32_bf16 v[90:93], v[138:141], v[186:189], v[90:93]
	v_mfma_f32_16x16x32_bf16 v[106:109], v[138:141], v[178:181], v[106:109]
	v_mfma_f32_16x16x32_bf16 v[106:109], v[142:145], v[182:185], v[106:109]
	v_mfma_f32_16x16x32_bf16 v[122:125], v[142:145], v[174:177], v[122:125]
	v_mfma_f32_16x16x32_bf16 v[122:125], v[138:141], v[170:173], v[122:125]
	v_mfma_f32_16x16x32_bf16 v[118:121], v[146:149], v[170:173], v[118:121]
	v_mfma_f32_16x16x32_bf16 v[118:121], v[150:153], v[174:177], v[118:121]
	v_mfma_f32_16x16x32_bf16 v[102:105], v[150:153], v[182:185], v[102:105]
	v_mfma_f32_16x16x32_bf16 v[102:105], v[146:149], v[178:181], v[102:105]
	v_mfma_f32_16x16x32_bf16 v[86:89], v[146:149], v[186:189], v[86:89]
	v_mfma_f32_16x16x32_bf16 v[86:89], v[150:153], v[190:193], v[86:89]
	v_mfma_f32_16x16x32_bf16 v[70:73], v[150:153], v[210:213], v[70:73]
	v_mfma_f32_16x16x32_bf16 v[70:73], v[146:149], v[206:209], v[70:73]
	v_mfma_f32_16x16x32_bf16 v[66:69], v[154:157], v[206:209], v[66:69]
	v_mfma_f32_16x16x32_bf16 v[66:69], v[166:169], v[210:213], v[66:69]
	v_mfma_f32_16x16x32_bf16 v[82:85], v[166:169], v[190:193], v[82:85]
	v_mfma_f32_16x16x32_bf16 v[82:85], v[154:157], v[186:189], v[82:85]
	v_mfma_f32_16x16x32_bf16 v[98:101], v[154:157], v[178:181], v[98:101]
	v_mfma_f32_16x16x32_bf16 v[98:101], v[166:169], v[182:185], v[98:101]
	v_mfma_f32_16x16x32_bf16 v[114:117], v[166:169], v[174:177], v[114:117]
	v_mfma_f32_16x16x32_bf16 v[114:117], v[154:157], v[170:173], v[114:117]
	s_barrier
	s_setprio 0
	s_add_i32 s30, s30, s39
	v_lshl_add_u64 v[202:203], s[20:21], 0, v[158:159]
	s_mov_b32 m0, s30
	s_nop 0
	global_load_lds_dwordx4 v[202:203], off
	s_add_i32 m0, s30, 0x2000
	s_add_u32 s30, s20, 0x80000
	v_lshl_add_u64 v[214:215], s[20:21], 0, v[160:161]
	s_addc_u32 s31, s21, 0
	s_add_i32 s42, s42, s39
	global_load_lds_dwordx4 v[214:215], off
	v_lshl_add_u64 v[216:217], s[30:31], 0, v[158:159]
	s_mov_b32 m0, s42
	v_lshl_add_u64 v[228:229], s[22:23], 0, v[160:161]
	global_load_lds_dwordx4 v[216:217], off
	v_lshl_add_u64 v[216:217], s[30:31], 0, v[160:161]
	s_add_i32 m0, s42, 0x2000
	s_nop 0
	global_load_lds_dwordx4 v[216:217], off
	v_lshl_add_u64 v[216:217], s[22:23], 0, v[158:159]
	s_mov_b32 m0, s87
	s_nop 0
	global_load_lds_dwordx4 v[216:217], off
	s_mov_b32 m0, s92
	s_nop 0
	global_load_lds_dwordx4 v[228:229], off
	ds_read_b128 v[170:173], v205 offset:16384
	ds_read_b128 v[174:177], v205 offset:17408
	ds_read_b128 v[178:181], v205 offset:18432
	ds_read_b128 v[182:185], v205 offset:19456
	ds_read_b128 v[186:189], v205 offset:20480
	ds_read_b128 v[190:193], v205 offset:21504
	ds_read_b128 v[206:209], v205 offset:22528
	ds_read_b128 v[210:213], v205 offset:23552


	s_waitcnt vmcnt(8)
	s_waitcnt lgkmcnt(0)
	s_setprio 1
	s_barrier
	v_mfma_f32_16x16x32_bf16 v[62:65], v[130:133], v[170:173], v[62:65]
	v_mfma_f32_16x16x32_bf16 v[62:65], v[134:137], v[174:177], v[62:65]
	v_mfma_f32_16x16x32_bf16 v[46:49], v[134:137], v[182:185], v[46:49]
	v_mfma_f32_16x16x32_bf16 v[46:49], v[130:133], v[178:181], v[46:49]
	v_mfma_f32_16x16x32_bf16 v[30:33], v[130:133], v[186:189], v[30:33]
	v_mfma_f32_16x16x32_bf16 v[30:33], v[134:137], v[190:193], v[30:33]
	v_mfma_f32_16x16x32_bf16 v[14:17], v[134:137], v[210:213], v[14:17]
	v_mfma_f32_16x16x32_bf16 v[14:17], v[130:133], v[206:209], v[14:17]
	v_mfma_f32_16x16x32_bf16 v[10:13], v[138:141], v[206:209], v[10:13]
	v_mfma_f32_16x16x32_bf16 v[10:13], v[142:145], v[210:213], v[10:13]
	v_mfma_f32_16x16x32_bf16 v[26:29], v[142:145], v[190:193], v[26:29]
	v_mfma_f32_16x16x32_bf16 v[26:29], v[138:141], v[186:189], v[26:29]
	v_mfma_f32_16x16x32_bf16 v[42:45], v[138:141], v[178:181], v[42:45]
	v_mfma_f32_16x16x32_bf16 v[42:45], v[142:145], v[182:185], v[42:45]
	v_mfma_f32_16x16x32_bf16 v[58:61], v[142:145], v[174:177], v[58:61]
	v_mfma_f32_16x16x32_bf16 v[58:61], v[138:141], v[170:173], v[58:61]
	v_mfma_f32_16x16x32_bf16 v[54:57], v[146:149], v[170:173], v[54:57]
	v_mfma_f32_16x16x32_bf16 v[54:57], v[150:153], v[174:177], v[54:57]
	v_mfma_f32_16x16x32_bf16 v[38:41], v[150:153], v[182:185], v[38:41]
	v_mfma_f32_16x16x32_bf16 v[38:41], v[146:149], v[178:181], v[38:41]
	v_mfma_f32_16x16x32_bf16 v[22:25], v[146:149], v[186:189], v[22:25]
	v_mfma_f32_16x16x32_bf16 v[22:25], v[150:153], v[190:193], v[22:25]
	v_mfma_f32_16x16x32_bf16 v[6:9], v[150:153], v[210:213], v[6:9]
	v_mfma_f32_16x16x32_bf16 v[6:9], v[146:149], v[206:209], v[6:9]
	v_mfma_f32_16x16x32_bf16 v[2:5], v[154:157], v[206:209], v[2:5]
	v_mfma_f32_16x16x32_bf16 v[2:5], v[166:169], v[210:213], v[2:5]
	v_mfma_f32_16x16x32_bf16 v[18:21], v[166:169], v[190:193], v[18:21]
	v_mfma_f32_16x16x32_bf16 v[18:21], v[154:157], v[186:189], v[18:21]
	v_mfma_f32_16x16x32_bf16 v[34:37], v[154:157], v[178:181], v[34:37]
	v_mfma_f32_16x16x32_bf16 v[34:37], v[166:169], v[182:185], v[34:37]
	v_mfma_f32_16x16x32_bf16 v[50:53], v[166:169], v[174:177], v[50:53]
	v_mfma_f32_16x16x32_bf16 v[50:53], v[154:157], v[170:173], v[50:53]
	s_barrier
	s_setprio 0
	s_add_i32 s30, 0, 0x18000
	s_add_i32 s31, 0, 0x1c000
	s_add_u32 s22, s22, 0x80000
	s_addc_u32 s23, s23, 0
	s_mov_b32 m0, s8
	v_lshl_add_u64 v[230:231], s[22:23], 0, v[158:159]
	global_load_lds_dwordx4 v[230:231], off
	v_lshl_add_u64 v[230:231], s[22:23], 0, v[160:161]
	s_mov_b32 m0, s9
	s_nop 0
	global_load_lds_dwordx4 v[230:231], off
	v_add_u32_e32 v142, s30, v204
	v_add_u32_e32 v166, s31, v204
	ds_read_b128 v[130:133], v142
	ds_read_b128 v[134:137], v142 offset:1024
	ds_read_b128 v[138:141], v142 offset:2048
	ds_read_b128 v[142:145], v142 offset:3072
	ds_read_b128 v[146:149], v166
	ds_read_b128 v[150:153], v166 offset:1024
	ds_read_b128 v[154:157], v166 offset:2048
	ds_read_b128 v[166:169], v166 offset:3072
	ds_read_b128 v[170:173], v205 offset:32768
	ds_read_b128 v[174:177], v205 offset:33792
	ds_read_b128 v[178:181], v205 offset:34816
	ds_read_b128 v[182:185], v205 offset:35840
	ds_read_b128 v[186:189], v205 offset:36864
	ds_read_b128 v[190:193], v205 offset:37888
	ds_read_b128 v[206:209], v205 offset:38912
	ds_read_b128 v[210:213], v205 offset:39936


	s_waitcnt vmcnt(8)
	s_waitcnt lgkmcnt(0)
	s_setprio 1
	s_barrier
	v_mfma_f32_16x16x32_bf16 v[126:129], v[130:133], v[170:173], v[126:129]
	v_mfma_f32_16x16x32_bf16 v[126:129], v[134:137], v[174:177], v[126:129]
	v_mfma_f32_16x16x32_bf16 v[110:113], v[134:137], v[182:185], v[110:113]
	v_mfma_f32_16x16x32_bf16 v[110:113], v[130:133], v[178:181], v[110:113]
	v_mfma_f32_16x16x32_bf16 v[94:97], v[130:133], v[186:189], v[94:97]
	v_mfma_f32_16x16x32_bf16 v[94:97], v[134:137], v[190:193], v[94:97]
	v_mfma_f32_16x16x32_bf16 v[78:81], v[134:137], v[210:213], v[78:81]
	v_mfma_f32_16x16x32_bf16 v[78:81], v[130:133], v[206:209], v[78:81]
	v_mfma_f32_16x16x32_bf16 v[74:77], v[138:141], v[206:209], v[74:77]
	v_mfma_f32_16x16x32_bf16 v[74:77], v[142:145], v[210:213], v[74:77]
	v_mfma_f32_16x16x32_bf16 v[90:93], v[142:145], v[190:193], v[90:93]
	v_mfma_f32_16x16x32_bf16 v[90:93], v[138:141], v[186:189], v[90:93]
	v_mfma_f32_16x16x32_bf16 v[106:109], v[138:141], v[178:181], v[106:109]
	v_mfma_f32_16x16x32_bf16 v[106:109], v[142:145], v[182:185], v[106:109]
	v_mfma_f32_16x16x32_bf16 v[122:125], v[142:145], v[174:177], v[122:125]
	v_mfma_f32_16x16x32_bf16 v[122:125], v[138:141], v[170:173], v[122:125]
	v_mfma_f32_16x16x32_bf16 v[118:121], v[146:149], v[170:173], v[118:121]
	v_mfma_f32_16x16x32_bf16 v[118:121], v[150:153], v[174:177], v[118:121]
	v_mfma_f32_16x16x32_bf16 v[102:105], v[150:153], v[182:185], v[102:105]
	v_mfma_f32_16x16x32_bf16 v[102:105], v[146:149], v[178:181], v[102:105]
	v_mfma_f32_16x16x32_bf16 v[86:89], v[146:149], v[186:189], v[86:89]
	v_mfma_f32_16x16x32_bf16 v[86:89], v[150:153], v[190:193], v[86:89]
	v_mfma_f32_16x16x32_bf16 v[70:73], v[150:153], v[210:213], v[70:73]
	v_mfma_f32_16x16x32_bf16 v[70:73], v[146:149], v[206:209], v[70:73]
	v_mfma_f32_16x16x32_bf16 v[66:69], v[154:157], v[206:209], v[66:69]
	v_mfma_f32_16x16x32_bf16 v[66:69], v[166:169], v[210:213], v[66:69]
	v_mfma_f32_16x16x32_bf16 v[82:85], v[166:169], v[190:193], v[82:85]
	v_mfma_f32_16x16x32_bf16 v[82:85], v[154:157], v[186:189], v[82:85]
	v_mfma_f32_16x16x32_bf16 v[98:101], v[154:157], v[178:181], v[98:101]
	v_mfma_f32_16x16x32_bf16 v[98:101], v[166:169], v[182:185], v[98:101]
	v_mfma_f32_16x16x32_bf16 v[114:117], v[166:169], v[174:177], v[114:117]
	v_mfma_f32_16x16x32_bf16 v[114:117], v[154:157], v[170:173], v[114:117]
	s_barrier
	s_setprio 0
	s_add_i32 s22, s30, s39
	v_lshl_add_u64 v[202:203], v[202:203], 0, s[10:11]
	s_mov_b32 m0, s22
	s_nop 0
	global_load_lds_dwordx4 v[202:203], off
	s_add_i32 m0, s22, 0x2000
	s_add_u32 s20, s20, 0x80080
	v_lshl_add_u64 v[202:203], v[214:215], 0, s[10:11]
	s_addc_u32 s21, s21, 0
	s_add_i32 s22, s31, s39
	global_load_lds_dwordx4 v[202:203], off
	v_lshl_add_u64 v[202:203], s[20:21], 0, v[158:159]
	s_mov_b32 m0, s22
	s_nop 0
	global_load_lds_dwordx4 v[202:203], off
	v_lshl_add_u64 v[202:203], s[20:21], 0, v[160:161]
	s_add_i32 m0, s22, 0x2000
	s_nop 0
	global_load_lds_dwordx4 v[202:203], off
	v_lshl_add_u64 v[202:203], v[216:217], 0, s[10:11]
	s_mov_b32 m0, s56
	s_nop 0
	global_load_lds_dwordx4 v[202:203], off
	v_lshl_add_u64 v[202:203], v[228:229], 0, s[10:11]
	s_mov_b32 m0, s57
	s_nop 0
	global_load_lds_dwordx4 v[202:203], off
	ds_read_b128 v[170:173], v205 offset:49152
	ds_read_b128 v[174:177], v205 offset:50176
	ds_read_b128 v[178:181], v205 offset:51200
	ds_read_b128 v[182:185], v205 offset:52224
	ds_read_b128 v[186:189], v205 offset:53248
	ds_read_b128 v[190:193], v205 offset:54272
	ds_read_b128 v[206:209], v205 offset:55296
	ds_read_b128 v[210:213], v205 offset:56320


	s_waitcnt vmcnt(8)
	s_waitcnt lgkmcnt(0)
	s_setprio 1
	s_barrier
	v_mfma_f32_16x16x32_bf16 v[62:65], v[130:133], v[170:173], v[62:65]
	v_mfma_f32_16x16x32_bf16 v[62:65], v[134:137], v[174:177], v[62:65]
	v_mfma_f32_16x16x32_bf16 v[46:49], v[134:137], v[182:185], v[46:49]
	v_mfma_f32_16x16x32_bf16 v[46:49], v[130:133], v[178:181], v[46:49]
	v_mfma_f32_16x16x32_bf16 v[30:33], v[130:133], v[186:189], v[30:33]
	v_mfma_f32_16x16x32_bf16 v[30:33], v[134:137], v[190:193], v[30:33]
	v_mfma_f32_16x16x32_bf16 v[14:17], v[134:137], v[210:213], v[14:17]
	v_mfma_f32_16x16x32_bf16 v[14:17], v[130:133], v[206:209], v[14:17]
	v_mfma_f32_16x16x32_bf16 v[10:13], v[138:141], v[206:209], v[10:13]
	v_mfma_f32_16x16x32_bf16 v[10:13], v[142:145], v[210:213], v[10:13]
	v_mfma_f32_16x16x32_bf16 v[26:29], v[142:145], v[190:193], v[26:29]
	v_mfma_f32_16x16x32_bf16 v[26:29], v[138:141], v[186:189], v[26:29]
	v_mfma_f32_16x16x32_bf16 v[42:45], v[138:141], v[178:181], v[42:45]
	v_mfma_f32_16x16x32_bf16 v[42:45], v[142:145], v[182:185], v[42:45]
	v_mfma_f32_16x16x32_bf16 v[58:61], v[142:145], v[174:177], v[58:61]
	v_mfma_f32_16x16x32_bf16 v[58:61], v[138:141], v[170:173], v[58:61]
	v_mfma_f32_16x16x32_bf16 v[54:57], v[146:149], v[170:173], v[54:57]
	v_mfma_f32_16x16x32_bf16 v[54:57], v[150:153], v[174:177], v[54:57]
	v_mfma_f32_16x16x32_bf16 v[38:41], v[150:153], v[182:185], v[38:41]
	v_mfma_f32_16x16x32_bf16 v[38:41], v[146:149], v[178:181], v[38:41]
	v_mfma_f32_16x16x32_bf16 v[22:25], v[146:149], v[186:189], v[22:25]
	v_mfma_f32_16x16x32_bf16 v[22:25], v[150:153], v[190:193], v[22:25]
	v_mfma_f32_16x16x32_bf16 v[6:9], v[150:153], v[210:213], v[6:9]
	v_mfma_f32_16x16x32_bf16 v[6:9], v[146:149], v[206:209], v[6:9]
	v_mfma_f32_16x16x32_bf16 v[2:5], v[154:157], v[206:209], v[2:5]
	v_mfma_f32_16x16x32_bf16 v[2:5], v[166:169], v[210:213], v[2:5]
	v_mfma_f32_16x16x32_bf16 v[18:21], v[166:169], v[190:193], v[18:21]
	v_mfma_f32_16x16x32_bf16 v[18:21], v[154:157], v[186:189], v[18:21]
	v_mfma_f32_16x16x32_bf16 v[34:37], v[154:157], v[178:181], v[34:37]
	v_mfma_f32_16x16x32_bf16 v[34:37], v[166:169], v[182:185], v[34:37]
	v_mfma_f32_16x16x32_bf16 v[50:53], v[166:169], v[174:177], v[50:53]
	v_mfma_f32_16x16x32_bf16 v[50:53], v[154:157], v[170:173], v[50:53]
	s_barrier
	s_setprio 0
	s_add_i32 s29, s29, 2
	s_add_u32 s18, s18, 0x100
	s_addc_u32 s19, s19, 0
	s_add_u32 s27, s27, 0x100
	s_addc_u32 s28, s28, 0
	s_cmp_gt_u32 s29, 29
	s_cbranch_scc0 .LBB0_364
	s_and_b64 vcc, exec, s[58:59]
	s_cbranch_vccz .LBB0_367
	s_barrier

.LBB0_1087:
	s_add_u32 s30, s28, 0xfff80080
	s_addc_u32 s31, s29, -1
	s_cmp_eq_u32 s83, 28
	s_cselect_b32 s43, s23, s31
	s_cselect_b32 s42, s44, s30
	s_cselect_b32 s31, s21, s82
	s_cselect_b32 s30, s45, s81
	s_add_i32 s84, 0, 0x10000
	s_add_i32 s86, 0, 0x14000
	v_lshl_add_u64 v[208:209], s[28:29], 0, v[204:205]
	s_add_i32 m0, s71, 0xc000
	s_nop 0
	global_load_lds_dwordx4 v[208:209], off
	v_lshl_add_u64 v[208:209], s[28:29], 0, v[206:207]
	s_add_i32 m0, s71, 0xe000
	s_nop 0
	global_load_lds_dwordx4 v[208:209], off
	v_add_u32_e32 v62, s84, v229
	v_add_u32_e32 v158, s86, v229
	ds_read_b128 v[42:45], v62
	ds_read_b128 v[46:49], v62 offset:1024
	ds_read_b128 v[58:61], v62 offset:2048
	ds_read_b128 v[62:65], v62 offset:3072
	ds_read_b128 v[146:149], v158
	ds_read_b128 v[150:153], v158 offset:1024
	ds_read_b128 v[154:157], v158 offset:2048
	ds_read_b128 v[158:161], v158 offset:3072
	ds_read_b128 v[162:165], v230
	ds_read_b128 v[166:169], v230 offset:1024
	ds_read_b128 v[170:173], v230 offset:2048
	ds_read_b128 v[174:177], v230 offset:3072
	ds_read_b128 v[178:181], v230 offset:4096
	ds_read_b128 v[182:185], v230 offset:5120
	ds_read_b128 v[186:189], v230 offset:6144
	ds_read_b128 v[190:193], v230 offset:7168


	s_waitcnt vmcnt(8)
	s_waitcnt lgkmcnt(0)
	s_setprio 1
	s_barrier
	v_mfma_f32_16x16x32_bf16 v[142:145], v[42:45], v[162:165], v[142:145]
	v_mfma_f32_16x16x32_bf16 v[142:145], v[46:49], v[166:169], v[142:145]
	v_mfma_f32_16x16x32_bf16 v[126:129], v[46:49], v[174:177], v[126:129]
	v_mfma_f32_16x16x32_bf16 v[126:129], v[42:45], v[170:173], v[126:129]
	v_mfma_f32_16x16x32_bf16 v[110:113], v[42:45], v[178:181], v[110:113]
	v_mfma_f32_16x16x32_bf16 v[110:113], v[46:49], v[182:185], v[110:113]
	v_mfma_f32_16x16x32_bf16 v[94:97], v[46:49], v[190:193], v[94:97]
	v_mfma_f32_16x16x32_bf16 v[94:97], v[42:45], v[186:189], v[94:97]
	v_mfma_f32_16x16x32_bf16 v[90:93], v[58:61], v[186:189], v[90:93]
	v_mfma_f32_16x16x32_bf16 v[90:93], v[62:65], v[190:193], v[90:93]
	v_mfma_f32_16x16x32_bf16 v[106:109], v[62:65], v[182:185], v[106:109]
	v_mfma_f32_16x16x32_bf16 v[106:109], v[58:61], v[178:181], v[106:109]
	v_mfma_f32_16x16x32_bf16 v[122:125], v[58:61], v[170:173], v[122:125]
	v_mfma_f32_16x16x32_bf16 v[122:125], v[62:65], v[174:177], v[122:125]
	v_mfma_f32_16x16x32_bf16 v[138:141], v[62:65], v[166:169], v[138:141]
	v_mfma_f32_16x16x32_bf16 v[138:141], v[58:61], v[162:165], v[138:141]
	v_mfma_f32_16x16x32_bf16 v[134:137], v[146:149], v[162:165], v[134:137]
	v_mfma_f32_16x16x32_bf16 v[134:137], v[150:153], v[166:169], v[134:137]
	v_mfma_f32_16x16x32_bf16 v[118:121], v[150:153], v[174:177], v[118:121]
	v_mfma_f32_16x16x32_bf16 v[118:121], v[146:149], v[170:173], v[118:121]
	v_mfma_f32_16x16x32_bf16 v[102:105], v[146:149], v[178:181], v[102:105]
	v_mfma_f32_16x16x32_bf16 v[102:105], v[150:153], v[182:185], v[102:105]
	v_mfma_f32_16x16x32_bf16 v[86:89], v[150:153], v[190:193], v[86:89]
	v_mfma_f32_16x16x32_bf16 v[86:89], v[146:149], v[186:189], v[86:89]
	v_mfma_f32_16x16x32_bf16 v[82:85], v[154:157], v[186:189], v[82:85]
	v_mfma_f32_16x16x32_bf16 v[82:85], v[158:161], v[190:193], v[82:85]
	v_mfma_f32_16x16x32_bf16 v[98:101], v[158:161], v[182:185], v[98:101]
	v_mfma_f32_16x16x32_bf16 v[98:101], v[154:157], v[178:181], v[98:101]
	v_mfma_f32_16x16x32_bf16 v[114:117], v[154:157], v[170:173], v[114:117]
	v_mfma_f32_16x16x32_bf16 v[114:117], v[158:161], v[174:177], v[114:117]
	v_mfma_f32_16x16x32_bf16 v[130:133], v[158:161], v[166:169], v[130:133]
	v_mfma_f32_16x16x32_bf16 v[130:133], v[154:157], v[162:165], v[130:133]
	s_barrier
	s_setprio 0
	s_add_i32 s84, s84, s70
	v_lshl_add_u64 v[208:209], s[30:31], 0, v[194:195]
	s_mov_b32 m0, s84
	s_nop 0
	global_load_lds_dwordx4 v[208:209], off
	s_add_i32 m0, s84, 0x2000
	s_add_u32 s84, s30, 0x80000
	v_lshl_add_u64 v[210:211], s[30:31], 0, v[202:203]
	s_addc_u32 s85, s31, 0
	s_add_i32 s86, s86, s70
	global_load_lds_dwordx4 v[210:211], off
	v_lshl_add_u64 v[212:213], s[84:85], 0, v[194:195]
	s_mov_b32 m0, s86
	v_lshl_add_u64 v[214:215], s[42:43], 0, v[202:203]
	global_load_lds_dwordx4 v[212:213], off
	v_lshl_add_u64 v[212:213], s[84:85], 0, v[202:203]
	s_add_i32 m0, s86, 0x2000
	s_nop 0
	global_load_lds_dwordx4 v[212:213], off
	v_lshl_add_u64 v[212:213], s[42:43], 0, v[194:195]
	s_mov_b32 m0, s71
	s_nop 0
	global_load_lds_dwordx4 v[212:213], off
	s_mov_b32 m0, s72
	s_nop 0
	global_load_lds_dwordx4 v[214:215], off
	ds_read_b128 v[162:165], v230 offset:16384
	ds_read_b128 v[166:169], v230 offset:17408
	ds_read_b128 v[170:173], v230 offset:18432
	ds_read_b128 v[174:177], v230 offset:19456
	ds_read_b128 v[178:181], v230 offset:20480
	ds_read_b128 v[182:185], v230 offset:21504
	ds_read_b128 v[186:189], v230 offset:22528
	ds_read_b128 v[190:193], v230 offset:23552


	s_waitcnt vmcnt(8)
	s_waitcnt lgkmcnt(0)
	s_setprio 1
	s_barrier
	v_mfma_f32_16x16x32_bf16 v[78:81], v[42:45], v[162:165], v[78:81]
	v_mfma_f32_16x16x32_bf16 v[78:81], v[46:49], v[166:169], v[78:81]
	v_mfma_f32_16x16x32_bf16 v[54:57], v[46:49], v[174:177], v[54:57]
	v_mfma_f32_16x16x32_bf16 v[54:57], v[42:45], v[170:173], v[54:57]
	v_mfma_f32_16x16x32_bf16 v[30:33], v[42:45], v[178:181], v[30:33]
	v_mfma_f32_16x16x32_bf16 v[30:33], v[46:49], v[182:185], v[30:33]
	v_mfma_f32_16x16x32_bf16 v[14:17], v[46:49], v[190:193], v[14:17]
	v_mfma_f32_16x16x32_bf16 v[14:17], v[42:45], v[186:189], v[14:17]
	v_mfma_f32_16x16x32_bf16 v[10:13], v[58:61], v[186:189], v[10:13]
	v_mfma_f32_16x16x32_bf16 v[10:13], v[62:65], v[190:193], v[10:13]
	v_mfma_f32_16x16x32_bf16 v[26:29], v[62:65], v[182:185], v[26:29]
	v_mfma_f32_16x16x32_bf16 v[26:29], v[58:61], v[178:181], v[26:29]
	v_mfma_f32_16x16x32_bf16 v[50:53], v[58:61], v[170:173], v[50:53]
	v_mfma_f32_16x16x32_bf16 v[50:53], v[62:65], v[174:177], v[50:53]
	v_mfma_f32_16x16x32_bf16 v[74:77], v[62:65], v[166:169], v[74:77]
	v_mfma_f32_16x16x32_bf16 v[74:77], v[58:61], v[162:165], v[74:77]
	v_mfma_f32_16x16x32_bf16 v[38:41], v[146:149], v[170:173], v[38:41]
	v_mfma_f32_16x16x32_bf16 v[34:37], v[154:157], v[170:173], v[34:37]
	v_mfma_f32_16x16x32_bf16 v[22:25], v[146:149], v[178:181], v[22:25]
	v_mfma_f32_16x16x32_bf16 v[18:21], v[154:157], v[178:181], v[18:21]
	v_mfma_f32_16x16x32_bf16 v[6:9], v[146:149], v[186:189], v[6:9]
	v_mfma_f32_16x16x32_bf16 v[2:5], v[154:157], v[186:189], v[2:5]
	v_mfma_f32_16x16x32_bf16 v[42:45], v[146:149], v[162:165], v[70:73]
	v_mfma_f32_16x16x32_bf16 v[46:49], v[154:157], v[162:165], v[66:69]
	v_mfma_f32_16x16x32_bf16 v[38:41], v[150:153], v[174:177], v[38:41]
	v_mfma_f32_16x16x32_bf16 v[34:37], v[158:161], v[174:177], v[34:37]
	v_mfma_f32_16x16x32_bf16 v[22:25], v[150:153], v[182:185], v[22:25]
	v_mfma_f32_16x16x32_bf16 v[18:21], v[158:161], v[182:185], v[18:21]
	v_mfma_f32_16x16x32_bf16 v[6:9], v[150:153], v[190:193], v[6:9]
	v_mfma_f32_16x16x32_bf16 v[2:5], v[158:161], v[190:193], v[2:5]
	v_mfma_f32_16x16x32_bf16 v[42:45], v[150:153], v[166:169], v[42:45]
	v_mfma_f32_16x16x32_bf16 v[46:49], v[158:161], v[166:169], v[46:49]
	s_barrier
	s_setprio 0
	s_add_i32 s84, 0, 0x18000
	s_add_i32 s85, 0, 0x1c000
	s_add_u32 s42, s42, 0x80000
	s_addc_u32 s43, s43, 0
	s_mov_b32 m0, s73
	v_lshl_add_u64 v[216:217], s[42:43], 0, v[194:195]
	global_load_lds_dwordx4 v[216:217], off
	v_lshl_add_u64 v[216:217], s[42:43], 0, v[202:203]
	s_mov_b32 m0, s74
	s_nop 0
	global_load_lds_dwordx4 v[216:217], off
	v_add_u32_e32 v70, s84, v229
	v_add_u32_e32 v158, s85, v229
	ds_read_b128 v[58:61], v70
	ds_read_b128 v[62:65], v70 offset:1024
	ds_read_b128 v[66:69], v70 offset:2048
	ds_read_b128 v[70:73], v70 offset:3072
	ds_read_b128 v[146:149], v158
	ds_read_b128 v[150:153], v158 offset:1024
	ds_read_b128 v[154:157], v158 offset:2048
	ds_read_b128 v[158:161], v158 offset:3072
	ds_read_b128 v[162:165], v230 offset:32768
	ds_read_b128 v[166:169], v230 offset:33792
	ds_read_b128 v[170:173], v230 offset:34816
	ds_read_b128 v[174:177], v230 offset:35840
	ds_read_b128 v[178:181], v230 offset:36864
	ds_read_b128 v[182:185], v230 offset:37888
	ds_read_b128 v[186:189], v230 offset:38912
	ds_read_b128 v[190:193], v230 offset:39936


	s_waitcnt vmcnt(8)
	s_waitcnt lgkmcnt(0)
	s_setprio 1
	s_barrier
	v_mfma_f32_16x16x32_bf16 v[142:145], v[58:61], v[162:165], v[142:145]
	v_mfma_f32_16x16x32_bf16 v[142:145], v[62:65], v[166:169], v[142:145]
	v_mfma_f32_16x16x32_bf16 v[126:129], v[62:65], v[174:177], v[126:129]
	v_mfma_f32_16x16x32_bf16 v[126:129], v[58:61], v[170:173], v[126:129]
	v_mfma_f32_16x16x32_bf16 v[110:113], v[58:61], v[178:181], v[110:113]
	v_mfma_f32_16x16x32_bf16 v[110:113], v[62:65], v[182:185], v[110:113]
	v_mfma_f32_16x16x32_bf16 v[94:97], v[62:65], v[190:193], v[94:97]
	v_mfma_f32_16x16x32_bf16 v[94:97], v[58:61], v[186:189], v[94:97]
	v_mfma_f32_16x16x32_bf16 v[90:93], v[66:69], v[186:189], v[90:93]
	v_mfma_f32_16x16x32_bf16 v[90:93], v[70:73], v[190:193], v[90:93]
	v_mfma_f32_16x16x32_bf16 v[106:109], v[70:73], v[182:185], v[106:109]
	v_mfma_f32_16x16x32_bf16 v[106:109], v[66:69], v[178:181], v[106:109]
	v_mfma_f32_16x16x32_bf16 v[122:125], v[66:69], v[170:173], v[122:125]
	v_mfma_f32_16x16x32_bf16 v[122:125], v[70:73], v[174:177], v[122:125]
	v_mfma_f32_16x16x32_bf16 v[138:141], v[70:73], v[166:169], v[138:141]
	v_mfma_f32_16x16x32_bf16 v[138:141], v[66:69], v[162:165], v[138:141]
	v_mfma_f32_16x16x32_bf16 v[134:137], v[146:149], v[162:165], v[134:137]
	v_mfma_f32_16x16x32_bf16 v[134:137], v[150:153], v[166:169], v[134:137]
	v_mfma_f32_16x16x32_bf16 v[118:121], v[150:153], v[174:177], v[118:121]
	v_mfma_f32_16x16x32_bf16 v[118:121], v[146:149], v[170:173], v[118:121]
	v_mfma_f32_16x16x32_bf16 v[102:105], v[146:149], v[178:181], v[102:105]
	v_mfma_f32_16x16x32_bf16 v[102:105], v[150:153], v[182:185], v[102:105]
	v_mfma_f32_16x16x32_bf16 v[86:89], v[150:153], v[190:193], v[86:89]
	v_mfma_f32_16x16x32_bf16 v[86:89], v[146:149], v[186:189], v[86:89]
	v_mfma_f32_16x16x32_bf16 v[82:85], v[154:157], v[186:189], v[82:85]
	v_mfma_f32_16x16x32_bf16 v[82:85], v[158:161], v[190:193], v[82:85]
	v_mfma_f32_16x16x32_bf16 v[98:101], v[158:161], v[182:185], v[98:101]
	v_mfma_f32_16x16x32_bf16 v[98:101], v[154:157], v[178:181], v[98:101]
	v_mfma_f32_16x16x32_bf16 v[114:117], v[154:157], v[170:173], v[114:117]
	v_mfma_f32_16x16x32_bf16 v[114:117], v[158:161], v[174:177], v[114:117]
	v_mfma_f32_16x16x32_bf16 v[130:133], v[158:161], v[166:169], v[130:133]
	v_mfma_f32_16x16x32_bf16 v[130:133], v[154:157], v[162:165], v[130:133]
	s_barrier
	s_setprio 0
	s_add_i32 s42, s84, s70
	v_lshl_add_u64 v[208:209], v[208:209], 0, s[10:11]
	s_mov_b32 m0, s42
	s_nop 0
	global_load_lds_dwordx4 v[208:209], off
	s_add_i32 m0, s42, 0x2000
	s_add_u32 s30, s30, 0x80080
	v_lshl_add_u64 v[208:209], v[210:211], 0, s[10:11]
	s_addc_u32 s31, s31, 0
	s_add_i32 s42, s85, s70
	global_load_lds_dwordx4 v[208:209], off
	v_lshl_add_u64 v[208:209], s[30:31], 0, v[194:195]
	s_mov_b32 m0, s42
	s_nop 0
	global_load_lds_dwordx4 v[208:209], off
	v_lshl_add_u64 v[208:209], s[30:31], 0, v[202:203]
	s_add_i32 m0, s42, 0x2000
	s_nop 0
	global_load_lds_dwordx4 v[208:209], off
	v_lshl_add_u64 v[208:209], v[212:213], 0, s[10:11]
	s_mov_b32 m0, s79
	s_nop 0
	global_load_lds_dwordx4 v[208:209], off
	v_lshl_add_u64 v[208:209], v[214:215], 0, s[10:11]
	s_mov_b32 m0, s80
	s_nop 0
	global_load_lds_dwordx4 v[208:209], off
	ds_read_b128 v[162:165], v230 offset:49152
	ds_read_b128 v[166:169], v230 offset:50176
	ds_read_b128 v[170:173], v230 offset:51200
	ds_read_b128 v[174:177], v230 offset:52224
	ds_read_b128 v[178:181], v230 offset:53248
	ds_read_b128 v[182:185], v230 offset:54272
	ds_read_b128 v[186:189], v230 offset:55296
	ds_read_b128 v[190:193], v230 offset:56320


	s_waitcnt vmcnt(8)
	s_waitcnt lgkmcnt(0)
	s_setprio 1
	s_barrier
	v_mfma_f32_16x16x32_bf16 v[78:81], v[58:61], v[162:165], v[78:81]
	v_mfma_f32_16x16x32_bf16 v[78:81], v[62:65], v[166:169], v[78:81]
	v_mfma_f32_16x16x32_bf16 v[54:57], v[62:65], v[174:177], v[54:57]
	v_mfma_f32_16x16x32_bf16 v[54:57], v[58:61], v[170:173], v[54:57]
	v_mfma_f32_16x16x32_bf16 v[30:33], v[58:61], v[178:181], v[30:33]
	v_mfma_f32_16x16x32_bf16 v[30:33], v[62:65], v[182:185], v[30:33]
	v_mfma_f32_16x16x32_bf16 v[14:17], v[62:65], v[190:193], v[14:17]
	v_mfma_f32_16x16x32_bf16 v[14:17], v[58:61], v[186:189], v[14:17]
	v_mfma_f32_16x16x32_bf16 v[10:13], v[66:69], v[186:189], v[10:13]
	v_mfma_f32_16x16x32_bf16 v[10:13], v[70:73], v[190:193], v[10:13]
	v_mfma_f32_16x16x32_bf16 v[26:29], v[70:73], v[182:185], v[26:29]
	v_mfma_f32_16x16x32_bf16 v[26:29], v[66:69], v[178:181], v[26:29]
	v_mfma_f32_16x16x32_bf16 v[50:53], v[66:69], v[170:173], v[50:53]
	v_mfma_f32_16x16x32_bf16 v[50:53], v[70:73], v[174:177], v[50:53]
	v_mfma_f32_16x16x32_bf16 v[74:77], v[70:73], v[166:169], v[74:77]
	v_mfma_f32_16x16x32_bf16 v[74:77], v[66:69], v[162:165], v[74:77]
	v_mfma_f32_16x16x32_bf16 v[42:45], v[146:149], v[162:165], v[42:45]
	v_mfma_f32_16x16x32_bf16 v[70:73], v[150:153], v[166:169], v[42:45]
	v_mfma_f32_16x16x32_bf16 v[42:45], v[154:157], v[162:165], v[46:49]
	v_mfma_f32_16x16x32_bf16 v[38:41], v[146:149], v[170:173], v[38:41]
	v_mfma_f32_16x16x32_bf16 v[34:37], v[154:157], v[170:173], v[34:37]
	v_mfma_f32_16x16x32_bf16 v[22:25], v[146:149], v[178:181], v[22:25]
	v_mfma_f32_16x16x32_bf16 v[18:21], v[154:157], v[178:181], v[18:21]
	v_mfma_f32_16x16x32_bf16 v[6:9], v[146:149], v[186:189], v[6:9]
	v_mfma_f32_16x16x32_bf16 v[2:5], v[154:157], v[186:189], v[2:5]
	v_mfma_f32_16x16x32_bf16 v[66:69], v[158:161], v[166:169], v[42:45]
	v_mfma_f32_16x16x32_bf16 v[38:41], v[150:153], v[174:177], v[38:41]
	v_mfma_f32_16x16x32_bf16 v[34:37], v[158:161], v[174:177], v[34:37]
	v_mfma_f32_16x16x32_bf16 v[22:25], v[150:153], v[182:185], v[22:25]
	v_mfma_f32_16x16x32_bf16 v[18:21], v[158:161], v[182:185], v[18:21]
	v_mfma_f32_16x16x32_bf16 v[6:9], v[150:153], v[190:193], v[6:9]
	v_mfma_f32_16x16x32_bf16 v[2:5], v[158:161], v[190:193], v[2:5]
	s_barrier
	s_setprio 0
	s_add_i32 s83, s83, 2
	s_add_u32 s28, s28, 0x100
	s_addc_u32 s29, s29, 0
	s_add_u32 s81, s81, 0x100
	s_addc_u32 s82, s82, 0
	s_cmp_gt_u32 s83, 29
	s_cbranch_scc0 .LBB0_1087
	s_and_b64 vcc, exec, s[16:17]
	s_cbranch_vccz .LBB0_1090
	s_barrier

.LBB0_1272:
	s_add_u32 s30, s28, 0xfff80080
	s_addc_u32 s31, s29, -1
	s_add_i32 s66, 0, 0x10000
	s_cmp_eq_u32 s65, 28
	s_cselect_b32 s37, s60, s31
	s_cselect_b32 s36, s61, s30
	s_cselect_b32 s31, s21, s64
	s_cselect_b32 s30, s62, s63
	s_add_i32 s68, 0, 0x14000
	v_lshl_add_u64 v[154:155], s[28:29], 0, v[150:151]
	s_add_i32 m0, s49, 0xc000
	s_nop 0
	global_load_lds_dwordx4 v[154:155], off
	v_lshl_add_u64 v[154:155], s[28:29], 0, v[152:153]
	s_add_i32 m0, s49, 0xe000
	s_nop 0
	global_load_lds_dwordx4 v[154:155], off
	v_add_u32_e32 v126, s66, v156
	v_add_u32_e32 v154, s68, v156
	ds_read_b128 v[114:117], v126
	ds_read_b128 v[118:121], v126 offset:1024
	ds_read_b128 v[122:125], v126 offset:2048
	ds_read_b128 v[126:129], v126 offset:3072
	ds_read_b128 v[158:161], v154
	ds_read_b128 v[162:165], v154 offset:1024
	ds_read_b128 v[166:169], v154 offset:2048
	ds_read_b128 v[170:173], v154 offset:3072
	ds_read_b128 v[174:177], v157
	ds_read_b128 v[178:181], v157 offset:1024
	ds_read_b128 v[182:185], v157 offset:2048
	ds_read_b128 v[186:189], v157 offset:3072
	ds_read_b128 v[190:193], v157 offset:4096
	ds_read_b128 v[202:205], v157 offset:5120
	ds_read_b128 v[206:209], v157 offset:6144
	ds_read_b128 v[210:213], v157 offset:7168


	s_waitcnt vmcnt(8)
	s_waitcnt lgkmcnt(0)
	s_setprio 1
	s_barrier
	v_mfma_f32_16x16x32_bf16 v[142:145], v[114:117], v[174:177], v[142:145]
	v_mfma_f32_16x16x32_bf16 v[142:145], v[118:121], v[178:181], v[142:145]
	v_mfma_f32_16x16x32_bf16 v[110:113], v[118:121], v[186:189], v[110:113]
	v_mfma_f32_16x16x32_bf16 v[110:113], v[114:117], v[182:185], v[110:113]
	v_mfma_f32_16x16x32_bf16 v[94:97], v[114:117], v[190:193], v[94:97]
	v_mfma_f32_16x16x32_bf16 v[94:97], v[118:121], v[202:205], v[94:97]
	v_mfma_f32_16x16x32_bf16 v[78:81], v[118:121], v[210:213], v[78:81]
	v_mfma_f32_16x16x32_bf16 v[78:81], v[114:117], v[206:209], v[78:81]
	v_mfma_f32_16x16x32_bf16 v[74:77], v[122:125], v[206:209], v[74:77]
	v_mfma_f32_16x16x32_bf16 v[74:77], v[126:129], v[210:213], v[74:77]
	v_mfma_f32_16x16x32_bf16 v[90:93], v[126:129], v[202:205], v[90:93]
	v_mfma_f32_16x16x32_bf16 v[90:93], v[122:125], v[190:193], v[90:93]
	v_mfma_f32_16x16x32_bf16 v[106:109], v[122:125], v[182:185], v[106:109]
	v_mfma_f32_16x16x32_bf16 v[106:109], v[126:129], v[186:189], v[106:109]
	v_mfma_f32_16x16x32_bf16 v[138:141], v[126:129], v[178:181], v[138:141]
	v_mfma_f32_16x16x32_bf16 v[138:141], v[122:125], v[174:177], v[138:141]
	v_mfma_f32_16x16x32_bf16 v[134:137], v[158:161], v[174:177], v[134:137]
	v_mfma_f32_16x16x32_bf16 v[134:137], v[162:165], v[178:181], v[134:137]
	v_mfma_f32_16x16x32_bf16 v[102:105], v[162:165], v[186:189], v[102:105]
	v_mfma_f32_16x16x32_bf16 v[102:105], v[158:161], v[182:185], v[102:105]
	v_mfma_f32_16x16x32_bf16 v[86:89], v[158:161], v[190:193], v[86:89]
	v_mfma_f32_16x16x32_bf16 v[86:89], v[162:165], v[202:205], v[86:89]
	v_mfma_f32_16x16x32_bf16 v[70:73], v[162:165], v[210:213], v[70:73]
	v_mfma_f32_16x16x32_bf16 v[70:73], v[158:161], v[206:209], v[70:73]
	v_mfma_f32_16x16x32_bf16 v[66:69], v[166:169], v[206:209], v[66:69]
	v_mfma_f32_16x16x32_bf16 v[66:69], v[170:173], v[210:213], v[66:69]
	v_mfma_f32_16x16x32_bf16 v[82:85], v[170:173], v[202:205], v[82:85]
	v_mfma_f32_16x16x32_bf16 v[82:85], v[166:169], v[190:193], v[82:85]
	v_mfma_f32_16x16x32_bf16 v[98:101], v[166:169], v[182:185], v[98:101]
	v_mfma_f32_16x16x32_bf16 v[98:101], v[170:173], v[186:189], v[98:101]
	v_mfma_f32_16x16x32_bf16 v[130:133], v[170:173], v[178:181], v[130:133]
	v_mfma_f32_16x16x32_bf16 v[130:133], v[166:169], v[174:177], v[130:133]
	s_barrier
	s_setprio 0
	s_add_i32 s66, s66, s48
	v_lshl_add_u64 v[154:155], s[30:31], 0, v[146:147]
	s_mov_b32 m0, s66
	s_nop 0
	global_load_lds_dwordx4 v[154:155], off
	s_add_i32 m0, s66, 0x2000
	s_add_u32 s66, s30, 0x80000
	v_lshl_add_u64 v[214:215], s[30:31], 0, v[148:149]
	s_addc_u32 s67, s31, 0
	s_add_i32 s68, s68, s48
	global_load_lds_dwordx4 v[214:215], off
	v_lshl_add_u64 v[216:217], s[66:67], 0, v[146:147]
	s_mov_b32 m0, s68
	v_lshl_add_u64 v[228:229], s[36:37], 0, v[148:149]
	global_load_lds_dwordx4 v[216:217], off
	v_lshl_add_u64 v[216:217], s[66:67], 0, v[148:149]
	s_add_i32 m0, s68, 0x2000
	s_nop 0
	global_load_lds_dwordx4 v[216:217], off
	v_lshl_add_u64 v[216:217], s[36:37], 0, v[146:147]
	s_mov_b32 m0, s49
	s_nop 0
	global_load_lds_dwordx4 v[216:217], off
	s_mov_b32 m0, s50
	s_nop 0
	global_load_lds_dwordx4 v[228:229], off
	ds_read_b128 v[174:177], v157 offset:16384
	ds_read_b128 v[178:181], v157 offset:17408
	ds_read_b128 v[182:185], v157 offset:18432
	ds_read_b128 v[186:189], v157 offset:19456
	ds_read_b128 v[190:193], v157 offset:20480
	ds_read_b128 v[202:205], v157 offset:21504
	ds_read_b128 v[206:209], v157 offset:22528
	ds_read_b128 v[210:213], v157 offset:23552


	s_waitcnt vmcnt(8)
	s_waitcnt lgkmcnt(0)
	s_setprio 1
	s_barrier
	v_mfma_f32_16x16x32_bf16 v[62:65], v[114:117], v[174:177], v[62:65]
	v_mfma_f32_16x16x32_bf16 v[62:65], v[118:121], v[178:181], v[62:65]
	v_mfma_f32_16x16x32_bf16 v[46:49], v[118:121], v[186:189], v[46:49]
	v_mfma_f32_16x16x32_bf16 v[46:49], v[114:117], v[182:185], v[46:49]
	v_mfma_f32_16x16x32_bf16 v[30:33], v[114:117], v[190:193], v[30:33]
	v_mfma_f32_16x16x32_bf16 v[30:33], v[118:121], v[202:205], v[30:33]
	v_mfma_f32_16x16x32_bf16 v[14:17], v[118:121], v[210:213], v[14:17]
	v_mfma_f32_16x16x32_bf16 v[14:17], v[114:117], v[206:209], v[14:17]
	v_mfma_f32_16x16x32_bf16 v[10:13], v[122:125], v[206:209], v[10:13]
	v_mfma_f32_16x16x32_bf16 v[10:13], v[126:129], v[210:213], v[10:13]
	v_mfma_f32_16x16x32_bf16 v[26:29], v[126:129], v[202:205], v[26:29]
	v_mfma_f32_16x16x32_bf16 v[26:29], v[122:125], v[190:193], v[26:29]
	v_mfma_f32_16x16x32_bf16 v[42:45], v[122:125], v[182:185], v[42:45]
	v_mfma_f32_16x16x32_bf16 v[42:45], v[126:129], v[186:189], v[42:45]
	v_mfma_f32_16x16x32_bf16 v[58:61], v[126:129], v[178:181], v[58:61]
	v_mfma_f32_16x16x32_bf16 v[58:61], v[122:125], v[174:177], v[58:61]
	v_mfma_f32_16x16x32_bf16 v[54:57], v[158:161], v[174:177], v[54:57]
	v_mfma_f32_16x16x32_bf16 v[54:57], v[162:165], v[178:181], v[54:57]
	v_mfma_f32_16x16x32_bf16 v[38:41], v[162:165], v[186:189], v[38:41]
	v_mfma_f32_16x16x32_bf16 v[38:41], v[158:161], v[182:185], v[38:41]
	v_mfma_f32_16x16x32_bf16 v[22:25], v[158:161], v[190:193], v[22:25]
	v_mfma_f32_16x16x32_bf16 v[22:25], v[162:165], v[202:205], v[22:25]
	v_mfma_f32_16x16x32_bf16 v[6:9], v[162:165], v[210:213], v[6:9]
	v_mfma_f32_16x16x32_bf16 v[6:9], v[158:161], v[206:209], v[6:9]
	v_mfma_f32_16x16x32_bf16 v[2:5], v[166:169], v[206:209], v[2:5]
	v_mfma_f32_16x16x32_bf16 v[2:5], v[170:173], v[210:213], v[2:5]
	v_mfma_f32_16x16x32_bf16 v[18:21], v[170:173], v[202:205], v[18:21]
	v_mfma_f32_16x16x32_bf16 v[18:21], v[166:169], v[190:193], v[18:21]
	v_mfma_f32_16x16x32_bf16 v[34:37], v[166:169], v[182:185], v[34:37]
	v_mfma_f32_16x16x32_bf16 v[34:37], v[170:173], v[186:189], v[34:37]
	v_mfma_f32_16x16x32_bf16 v[50:53], v[170:173], v[178:181], v[50:53]
	v_mfma_f32_16x16x32_bf16 v[50:53], v[166:169], v[174:177], v[50:53]
	s_barrier
	s_setprio 0
	s_add_i32 s66, 0, 0x18000
	s_add_i32 s67, 0, 0x1c000
	s_add_u32 s36, s36, 0x80000
	s_addc_u32 s37, s37, 0
	s_mov_b32 m0, s51
	v_lshl_add_u64 v[230:231], s[36:37], 0, v[146:147]
	global_load_lds_dwordx4 v[230:231], off
	v_lshl_add_u64 v[230:231], s[36:37], 0, v[148:149]
	s_mov_b32 m0, s52
	s_nop 0
	global_load_lds_dwordx4 v[230:231], off
	v_add_u32_e32 v126, s66, v156
	v_add_u32_e32 v170, s67, v156
	ds_read_b128 v[114:117], v126
	ds_read_b128 v[118:121], v126 offset:1024
	ds_read_b128 v[122:125], v126 offset:2048
	ds_read_b128 v[126:129], v126 offset:3072
	ds_read_b128 v[158:161], v170
	ds_read_b128 v[162:165], v170 offset:1024
	ds_read_b128 v[166:169], v170 offset:2048
	ds_read_b128 v[170:173], v170 offset:3072
	ds_read_b128 v[174:177], v157 offset:32768
	ds_read_b128 v[178:181], v157 offset:33792
	ds_read_b128 v[182:185], v157 offset:34816
	ds_read_b128 v[186:189], v157 offset:35840
	ds_read_b128 v[190:193], v157 offset:36864
	ds_read_b128 v[202:205], v157 offset:37888
	ds_read_b128 v[206:209], v157 offset:38912
	ds_read_b128 v[210:213], v157 offset:39936


	s_waitcnt vmcnt(8)
	s_waitcnt lgkmcnt(0)
	s_setprio 1
	s_barrier
	v_mfma_f32_16x16x32_bf16 v[142:145], v[114:117], v[174:177], v[142:145]
	v_mfma_f32_16x16x32_bf16 v[142:145], v[118:121], v[178:181], v[142:145]
	v_mfma_f32_16x16x32_bf16 v[110:113], v[118:121], v[186:189], v[110:113]
	v_mfma_f32_16x16x32_bf16 v[110:113], v[114:117], v[182:185], v[110:113]
	v_mfma_f32_16x16x32_bf16 v[94:97], v[114:117], v[190:193], v[94:97]
	v_mfma_f32_16x16x32_bf16 v[94:97], v[118:121], v[202:205], v[94:97]
	v_mfma_f32_16x16x32_bf16 v[78:81], v[118:121], v[210:213], v[78:81]
	v_mfma_f32_16x16x32_bf16 v[78:81], v[114:117], v[206:209], v[78:81]
	v_mfma_f32_16x16x32_bf16 v[74:77], v[122:125], v[206:209], v[74:77]
	v_mfma_f32_16x16x32_bf16 v[74:77], v[126:129], v[210:213], v[74:77]
	v_mfma_f32_16x16x32_bf16 v[90:93], v[126:129], v[202:205], v[90:93]
	v_mfma_f32_16x16x32_bf16 v[90:93], v[122:125], v[190:193], v[90:93]
	v_mfma_f32_16x16x32_bf16 v[106:109], v[122:125], v[182:185], v[106:109]
	v_mfma_f32_16x16x32_bf16 v[106:109], v[126:129], v[186:189], v[106:109]
	v_mfma_f32_16x16x32_bf16 v[138:141], v[126:129], v[178:181], v[138:141]
	v_mfma_f32_16x16x32_bf16 v[138:141], v[122:125], v[174:177], v[138:141]
	v_mfma_f32_16x16x32_bf16 v[134:137], v[158:161], v[174:177], v[134:137]
	v_mfma_f32_16x16x32_bf16 v[134:137], v[162:165], v[178:181], v[134:137]
	v_mfma_f32_16x16x32_bf16 v[102:105], v[162:165], v[186:189], v[102:105]
	v_mfma_f32_16x16x32_bf16 v[102:105], v[158:161], v[182:185], v[102:105]
	v_mfma_f32_16x16x32_bf16 v[86:89], v[158:161], v[190:193], v[86:89]
	v_mfma_f32_16x16x32_bf16 v[86:89], v[162:165], v[202:205], v[86:89]
	v_mfma_f32_16x16x32_bf16 v[70:73], v[162:165], v[210:213], v[70:73]
	v_mfma_f32_16x16x32_bf16 v[70:73], v[158:161], v[206:209], v[70:73]
	v_mfma_f32_16x16x32_bf16 v[66:69], v[166:169], v[206:209], v[66:69]
	v_mfma_f32_16x16x32_bf16 v[66:69], v[170:173], v[210:213], v[66:69]
	v_mfma_f32_16x16x32_bf16 v[82:85], v[170:173], v[202:205], v[82:85]
	v_mfma_f32_16x16x32_bf16 v[82:85], v[166:169], v[190:193], v[82:85]
	v_mfma_f32_16x16x32_bf16 v[98:101], v[166:169], v[182:185], v[98:101]
	v_mfma_f32_16x16x32_bf16 v[98:101], v[170:173], v[186:189], v[98:101]
	v_mfma_f32_16x16x32_bf16 v[130:133], v[170:173], v[178:181], v[130:133]
	v_mfma_f32_16x16x32_bf16 v[130:133], v[166:169], v[174:177], v[130:133]
	s_barrier
	s_setprio 0
	s_add_i32 s36, s66, s48
	v_lshl_add_u64 v[154:155], v[154:155], 0, s[10:11]
	s_mov_b32 m0, s36
	s_nop 0
	global_load_lds_dwordx4 v[154:155], off
	s_add_i32 m0, s36, 0x2000
	s_add_u32 s30, s30, 0x80080
	v_lshl_add_u64 v[154:155], v[214:215], 0, s[10:11]
	s_addc_u32 s31, s31, 0
	s_add_i32 s36, s67, s48
	global_load_lds_dwordx4 v[154:155], off
	v_lshl_add_u64 v[154:155], s[30:31], 0, v[146:147]
	s_mov_b32 m0, s36
	s_nop 0
	global_load_lds_dwordx4 v[154:155], off
	v_lshl_add_u64 v[154:155], s[30:31], 0, v[148:149]
	s_add_i32 m0, s36, 0x2000
	s_nop 0
	global_load_lds_dwordx4 v[154:155], off
	v_lshl_add_u64 v[154:155], v[216:217], 0, s[10:11]
	s_mov_b32 m0, s53
	s_nop 0
	global_load_lds_dwordx4 v[154:155], off
	v_lshl_add_u64 v[154:155], v[228:229], 0, s[10:11]
	s_mov_b32 m0, s56
	s_nop 0
	global_load_lds_dwordx4 v[154:155], off
	ds_read_b128 v[174:177], v157 offset:49152
	ds_read_b128 v[178:181], v157 offset:50176
	ds_read_b128 v[182:185], v157 offset:51200
	ds_read_b128 v[186:189], v157 offset:52224
	ds_read_b128 v[190:193], v157 offset:53248
	ds_read_b128 v[202:205], v157 offset:54272
	ds_read_b128 v[206:209], v157 offset:55296
	ds_read_b128 v[210:213], v157 offset:56320


	s_waitcnt vmcnt(8)
	s_waitcnt lgkmcnt(0)
	s_setprio 1
	s_barrier
	v_mfma_f32_16x16x32_bf16 v[62:65], v[114:117], v[174:177], v[62:65]
	v_mfma_f32_16x16x32_bf16 v[62:65], v[118:121], v[178:181], v[62:65]
	v_mfma_f32_16x16x32_bf16 v[46:49], v[118:121], v[186:189], v[46:49]
	v_mfma_f32_16x16x32_bf16 v[46:49], v[114:117], v[182:185], v[46:49]
	v_mfma_f32_16x16x32_bf16 v[30:33], v[114:117], v[190:193], v[30:33]
	v_mfma_f32_16x16x32_bf16 v[30:33], v[118:121], v[202:205], v[30:33]
	v_mfma_f32_16x16x32_bf16 v[14:17], v[118:121], v[210:213], v[14:17]
	v_mfma_f32_16x16x32_bf16 v[14:17], v[114:117], v[206:209], v[14:17]
	v_mfma_f32_16x16x32_bf16 v[10:13], v[122:125], v[206:209], v[10:13]
	v_mfma_f32_16x16x32_bf16 v[10:13], v[126:129], v[210:213], v[10:13]
	v_mfma_f32_16x16x32_bf16 v[26:29], v[126:129], v[202:205], v[26:29]
	v_mfma_f32_16x16x32_bf16 v[26:29], v[122:125], v[190:193], v[26:29]
	v_mfma_f32_16x16x32_bf16 v[42:45], v[122:125], v[182:185], v[42:45]
	v_mfma_f32_16x16x32_bf16 v[42:45], v[126:129], v[186:189], v[42:45]
	v_mfma_f32_16x16x32_bf16 v[58:61], v[126:129], v[178:181], v[58:61]
	v_mfma_f32_16x16x32_bf16 v[58:61], v[122:125], v[174:177], v[58:61]
	v_mfma_f32_16x16x32_bf16 v[54:57], v[158:161], v[174:177], v[54:57]
	v_mfma_f32_16x16x32_bf16 v[54:57], v[162:165], v[178:181], v[54:57]
	v_mfma_f32_16x16x32_bf16 v[38:41], v[162:165], v[186:189], v[38:41]
	v_mfma_f32_16x16x32_bf16 v[38:41], v[158:161], v[182:185], v[38:41]
	v_mfma_f32_16x16x32_bf16 v[22:25], v[158:161], v[190:193], v[22:25]
	v_mfma_f32_16x16x32_bf16 v[22:25], v[162:165], v[202:205], v[22:25]
	v_mfma_f32_16x16x32_bf16 v[6:9], v[162:165], v[210:213], v[6:9]
	v_mfma_f32_16x16x32_bf16 v[6:9], v[158:161], v[206:209], v[6:9]
	v_mfma_f32_16x16x32_bf16 v[2:5], v[166:169], v[206:209], v[2:5]
	v_mfma_f32_16x16x32_bf16 v[2:5], v[170:173], v[210:213], v[2:5]
	v_mfma_f32_16x16x32_bf16 v[18:21], v[170:173], v[202:205], v[18:21]
	v_mfma_f32_16x16x32_bf16 v[18:21], v[166:169], v[190:193], v[18:21]
	v_mfma_f32_16x16x32_bf16 v[34:37], v[166:169], v[182:185], v[34:37]
	v_mfma_f32_16x16x32_bf16 v[34:37], v[170:173], v[186:189], v[34:37]
	v_mfma_f32_16x16x32_bf16 v[50:53], v[170:173], v[178:181], v[50:53]
	v_mfma_f32_16x16x32_bf16 v[50:53], v[166:169], v[174:177], v[50:53]
	s_barrier
	s_setprio 0
	s_add_i32 s65, s65, 2
	s_add_u32 s28, s28, 0x100
	s_addc_u32 s29, s29, 0
	s_add_u32 s63, s63, 0x100
	s_addc_u32 s64, s64, 0
	s_cmp_gt_u32 s65, 29
	s_cbranch_scc0 .LBB0_1272
	s_and_b64 vcc, exec, s[18:19]
	s_cbranch_vccz .LBB0_1275
	s_barrier

.LBB0_1346:
	s_or_b32 s20, s30, 1
	s_mul_hi_u32 s31, s20, 0x280000
	s_mul_i32 s42, s20, 0x280000
	s_add_u32 s20, s56, s18
	s_addc_u32 s21, s57, s19
	s_add_u32 s18, s16, 0x280000
	s_addc_u32 s19, s17, 0
	s_add_i32 s44, 0, 0x10000
	s_add_i32 s45, 0, 0x14000
	s_add_u32 s42, s62, s42
	s_addc_u32 s43, s63, s31
	v_lshl_add_u64 v[206:207], s[42:43], 0, v[194:195]
	s_add_i32 m0, s24, 0xc000
	s_nop 0
	global_load_lds_dwordx4 v[206:207], off
	v_lshl_add_u64 v[206:207], s[42:43], 0, v[42:43]
	s_add_i32 m0, s24, 0xe000
	s_nop 0
	global_load_lds_dwordx4 v[206:207], off
	v_add_u32_e32 v146, s44, v44
	v_add_u32_e32 v162, s45, v44
	ds_read_b128 v[46:49], v146
	ds_read_b128 v[58:61], v146 offset:1024
	ds_read_b128 v[62:65], v146 offset:2048
	ds_read_b128 v[146:149], v146 offset:3072
	ds_read_b128 v[150:153], v162
	ds_read_b128 v[154:157], v162 offset:1024
	ds_read_b128 v[158:161], v162 offset:2048
	ds_read_b128 v[162:165], v162 offset:3072
	ds_read_b128 v[166:169], v45
	ds_read_b128 v[170:173], v45 offset:1024
	ds_read_b128 v[174:177], v45 offset:2048
	ds_read_b128 v[178:181], v45 offset:3072
	ds_read_b128 v[182:185], v45 offset:4096
	ds_read_b128 v[186:189], v45 offset:5120
	ds_read_b128 v[190:193], v45 offset:6144
	ds_read_b128 v[202:205], v45 offset:7168


	s_waitcnt vmcnt(8)
	s_waitcnt lgkmcnt(0)
	s_setprio 1
	s_barrier
	v_mfma_f32_16x16x32_bf16 v[142:145], v[46:49], v[166:169], v[142:145]
	v_mfma_f32_16x16x32_bf16 v[142:145], v[58:61], v[170:173], v[142:145]
	v_mfma_f32_16x16x32_bf16 v[126:129], v[58:61], v[178:181], v[126:129]
	v_mfma_f32_16x16x32_bf16 v[126:129], v[46:49], v[174:177], v[126:129]
	v_mfma_f32_16x16x32_bf16 v[110:113], v[46:49], v[182:185], v[110:113]
	v_mfma_f32_16x16x32_bf16 v[110:113], v[58:61], v[186:189], v[110:113]
	v_mfma_f32_16x16x32_bf16 v[94:97], v[58:61], v[202:205], v[94:97]
	v_mfma_f32_16x16x32_bf16 v[94:97], v[46:49], v[190:193], v[94:97]
	v_mfma_f32_16x16x32_bf16 v[90:93], v[62:65], v[190:193], v[90:93]
	v_mfma_f32_16x16x32_bf16 v[90:93], v[146:149], v[202:205], v[90:93]
	v_mfma_f32_16x16x32_bf16 v[106:109], v[146:149], v[186:189], v[106:109]
	v_mfma_f32_16x16x32_bf16 v[106:109], v[62:65], v[182:185], v[106:109]
	v_mfma_f32_16x16x32_bf16 v[122:125], v[62:65], v[174:177], v[122:125]
	v_mfma_f32_16x16x32_bf16 v[122:125], v[146:149], v[178:181], v[122:125]
	v_mfma_f32_16x16x32_bf16 v[138:141], v[146:149], v[170:173], v[138:141]
	v_mfma_f32_16x16x32_bf16 v[138:141], v[62:65], v[166:169], v[138:141]
	v_mfma_f32_16x16x32_bf16 v[134:137], v[150:153], v[166:169], v[134:137]
	v_mfma_f32_16x16x32_bf16 v[134:137], v[154:157], v[170:173], v[134:137]
	v_mfma_f32_16x16x32_bf16 v[118:121], v[154:157], v[178:181], v[118:121]
	v_mfma_f32_16x16x32_bf16 v[118:121], v[150:153], v[174:177], v[118:121]
	v_mfma_f32_16x16x32_bf16 v[102:105], v[150:153], v[182:185], v[102:105]
	v_mfma_f32_16x16x32_bf16 v[102:105], v[154:157], v[186:189], v[102:105]
	v_mfma_f32_16x16x32_bf16 v[86:89], v[154:157], v[202:205], v[86:89]
	v_mfma_f32_16x16x32_bf16 v[86:89], v[150:153], v[190:193], v[86:89]
	v_mfma_f32_16x16x32_bf16 v[82:85], v[158:161], v[190:193], v[82:85]
	v_mfma_f32_16x16x32_bf16 v[82:85], v[162:165], v[202:205], v[82:85]
	v_mfma_f32_16x16x32_bf16 v[98:101], v[162:165], v[186:189], v[98:101]
	v_mfma_f32_16x16x32_bf16 v[98:101], v[158:161], v[182:185], v[98:101]
	v_mfma_f32_16x16x32_bf16 v[114:117], v[158:161], v[174:177], v[114:117]
	v_mfma_f32_16x16x32_bf16 v[114:117], v[162:165], v[178:181], v[114:117]
	v_mfma_f32_16x16x32_bf16 v[130:133], v[162:165], v[170:173], v[130:133]
	v_mfma_f32_16x16x32_bf16 v[130:133], v[158:161], v[166:169], v[130:133]
	s_barrier
	s_setprio 0
	s_add_i32 s31, s44, s23
	v_lshl_add_u64 v[206:207], s[20:21], 0, v[194:195]
	s_mov_b32 m0, s31
	s_nop 0
	global_load_lds_dwordx4 v[206:207], off
	s_add_i32 m0, s31, 0x2000
	s_add_u32 s42, s20, 0x4000
	v_lshl_add_u64 v[206:207], s[20:21], 0, v[42:43]
	s_addc_u32 s43, s21, 0
	s_add_i32 s31, s45, s23
	global_load_lds_dwordx4 v[206:207], off
	v_lshl_add_u64 v[206:207], s[42:43], 0, v[194:195]
	s_mov_b32 m0, s31
	s_nop 0
	global_load_lds_dwordx4 v[206:207], off
	v_lshl_add_u64 v[206:207], s[42:43], 0, v[42:43]
	s_add_i32 m0, s31, 0x2000
	s_nop 0
	global_load_lds_dwordx4 v[206:207], off
	v_lshl_add_u64 v[206:207], s[16:17], 0, v[194:195]
	s_mov_b32 m0, s24
	s_nop 0
	global_load_lds_dwordx4 v[206:207], off
	v_lshl_add_u64 v[206:207], s[16:17], 0, v[42:43]
	s_mov_b32 m0, s25
	s_nop 0
	global_load_lds_dwordx4 v[206:207], off
	ds_read_b128 v[166:169], v45 offset:16384
	ds_read_b128 v[170:173], v45 offset:17408
	ds_read_b128 v[174:177], v45 offset:18432
	ds_read_b128 v[178:181], v45 offset:19456
	ds_read_b128 v[182:185], v45 offset:20480
	ds_read_b128 v[186:189], v45 offset:21504
	ds_read_b128 v[190:193], v45 offset:22528
	ds_read_b128 v[202:205], v45 offset:23552


	s_waitcnt vmcnt(8)
	s_waitcnt lgkmcnt(0)
	s_setprio 1
	s_barrier
	v_mfma_f32_16x16x32_bf16 v[78:81], v[46:49], v[166:169], v[78:81]
	v_mfma_f32_16x16x32_bf16 v[78:81], v[58:61], v[170:173], v[78:81]
	v_mfma_f32_16x16x32_bf16 v[54:57], v[58:61], v[178:181], v[54:57]
	v_mfma_f32_16x16x32_bf16 v[54:57], v[46:49], v[174:177], v[54:57]
	v_mfma_f32_16x16x32_bf16 v[30:33], v[46:49], v[182:185], v[30:33]
	v_mfma_f32_16x16x32_bf16 v[30:33], v[58:61], v[186:189], v[30:33]
	v_mfma_f32_16x16x32_bf16 v[14:17], v[58:61], v[202:205], v[14:17]
	v_mfma_f32_16x16x32_bf16 v[14:17], v[46:49], v[190:193], v[14:17]
	v_mfma_f32_16x16x32_bf16 v[10:13], v[62:65], v[190:193], v[10:13]
	v_mfma_f32_16x16x32_bf16 v[10:13], v[146:149], v[202:205], v[10:13]
	v_mfma_f32_16x16x32_bf16 v[26:29], v[146:149], v[186:189], v[26:29]
	v_mfma_f32_16x16x32_bf16 v[26:29], v[62:65], v[182:185], v[26:29]
	v_mfma_f32_16x16x32_bf16 v[50:53], v[62:65], v[174:177], v[50:53]
	v_mfma_f32_16x16x32_bf16 v[50:53], v[146:149], v[178:181], v[50:53]
	v_mfma_f32_16x16x32_bf16 v[74:77], v[146:149], v[170:173], v[74:77]
	v_mfma_f32_16x16x32_bf16 v[74:77], v[62:65], v[166:169], v[74:77]
	v_mfma_f32_16x16x32_bf16 v[38:41], v[150:153], v[174:177], v[38:41]
	v_mfma_f32_16x16x32_bf16 v[34:37], v[158:161], v[174:177], v[34:37]
	v_mfma_f32_16x16x32_bf16 v[22:25], v[150:153], v[182:185], v[22:25]
	v_mfma_f32_16x16x32_bf16 v[18:21], v[158:161], v[182:185], v[18:21]
	v_mfma_f32_16x16x32_bf16 v[6:9], v[150:153], v[190:193], v[6:9]
	v_mfma_f32_16x16x32_bf16 v[2:5], v[158:161], v[190:193], v[2:5]
	v_mfma_f32_16x16x32_bf16 v[46:49], v[150:153], v[166:169], v[70:73]
	v_mfma_f32_16x16x32_bf16 v[58:61], v[158:161], v[166:169], v[66:69]
	v_mfma_f32_16x16x32_bf16 v[38:41], v[154:157], v[178:181], v[38:41]
	v_mfma_f32_16x16x32_bf16 v[34:37], v[162:165], v[178:181], v[34:37]
	v_mfma_f32_16x16x32_bf16 v[22:25], v[154:157], v[186:189], v[22:25]
	v_mfma_f32_16x16x32_bf16 v[18:21], v[162:165], v[186:189], v[18:21]
	v_mfma_f32_16x16x32_bf16 v[6:9], v[154:157], v[202:205], v[6:9]
	v_mfma_f32_16x16x32_bf16 v[2:5], v[162:165], v[202:205], v[2:5]
	v_mfma_f32_16x16x32_bf16 v[46:49], v[154:157], v[170:173], v[46:49]
	v_mfma_f32_16x16x32_bf16 v[58:61], v[162:165], v[170:173], v[58:61]
	s_barrier
	s_setprio 0
	s_add_i32 s31, 0, 0x18000
	s_add_i32 s42, 0, 0x1c000
	s_add_u32 s16, s16, 0x4000
	s_addc_u32 s17, s17, 0
	s_mov_b32 m0, s26
	v_lshl_add_u64 v[206:207], s[16:17], 0, v[194:195]
	global_load_lds_dwordx4 v[206:207], off
	v_lshl_add_u64 v[206:207], s[16:17], 0, v[42:43]
	s_mov_b32 m0, s27
	s_nop 0
	global_load_lds_dwordx4 v[206:207], off
	v_add_u32_e32 v146, s31, v44
	v_add_u32_e32 v162, s42, v44
	ds_read_b128 v[62:65], v146
	ds_read_b128 v[66:69], v146 offset:1024
	ds_read_b128 v[70:73], v146 offset:2048
	ds_read_b128 v[146:149], v146 offset:3072
	ds_read_b128 v[150:153], v162
	ds_read_b128 v[154:157], v162 offset:1024
	ds_read_b128 v[158:161], v162 offset:2048
	ds_read_b128 v[162:165], v162 offset:3072
	ds_read_b128 v[166:169], v45 offset:32768
	ds_read_b128 v[170:173], v45 offset:33792
	ds_read_b128 v[174:177], v45 offset:34816
	ds_read_b128 v[178:181], v45 offset:35840
	ds_read_b128 v[182:185], v45 offset:36864
	ds_read_b128 v[186:189], v45 offset:37888
	ds_read_b128 v[190:193], v45 offset:38912
	ds_read_b128 v[202:205], v45 offset:39936


	s_waitcnt vmcnt(8)
	s_waitcnt lgkmcnt(0)
	s_setprio 1
	s_barrier
	v_mfma_f32_16x16x32_bf16 v[142:145], v[62:65], v[166:169], v[142:145]
	v_mfma_f32_16x16x32_bf16 v[142:145], v[66:69], v[170:173], v[142:145]
	v_mfma_f32_16x16x32_bf16 v[126:129], v[66:69], v[178:181], v[126:129]
	v_mfma_f32_16x16x32_bf16 v[126:129], v[62:65], v[174:177], v[126:129]
	v_mfma_f32_16x16x32_bf16 v[110:113], v[62:65], v[182:185], v[110:113]
	v_mfma_f32_16x16x32_bf16 v[110:113], v[66:69], v[186:189], v[110:113]
	v_mfma_f32_16x16x32_bf16 v[94:97], v[66:69], v[202:205], v[94:97]
	v_mfma_f32_16x16x32_bf16 v[94:97], v[62:65], v[190:193], v[94:97]
	v_mfma_f32_16x16x32_bf16 v[90:93], v[70:73], v[190:193], v[90:93]
	v_mfma_f32_16x16x32_bf16 v[90:93], v[146:149], v[202:205], v[90:93]
	v_mfma_f32_16x16x32_bf16 v[106:109], v[146:149], v[186:189], v[106:109]
	v_mfma_f32_16x16x32_bf16 v[106:109], v[70:73], v[182:185], v[106:109]
	v_mfma_f32_16x16x32_bf16 v[122:125], v[70:73], v[174:177], v[122:125]
	v_mfma_f32_16x16x32_bf16 v[122:125], v[146:149], v[178:181], v[122:125]
	v_mfma_f32_16x16x32_bf16 v[138:141], v[146:149], v[170:173], v[138:141]
	v_mfma_f32_16x16x32_bf16 v[138:141], v[70:73], v[166:169], v[138:141]
	v_mfma_f32_16x16x32_bf16 v[134:137], v[150:153], v[166:169], v[134:137]
	v_mfma_f32_16x16x32_bf16 v[134:137], v[154:157], v[170:173], v[134:137]
	v_mfma_f32_16x16x32_bf16 v[118:121], v[154:157], v[178:181], v[118:121]
	v_mfma_f32_16x16x32_bf16 v[118:121], v[150:153], v[174:177], v[118:121]
	v_mfma_f32_16x16x32_bf16 v[102:105], v[150:153], v[182:185], v[102:105]
	v_mfma_f32_16x16x32_bf16 v[102:105], v[154:157], v[186:189], v[102:105]
	v_mfma_f32_16x16x32_bf16 v[86:89], v[154:157], v[202:205], v[86:89]
	v_mfma_f32_16x16x32_bf16 v[86:89], v[150:153], v[190:193], v[86:89]
	v_mfma_f32_16x16x32_bf16 v[82:85], v[158:161], v[190:193], v[82:85]
	v_mfma_f32_16x16x32_bf16 v[82:85], v[162:165], v[202:205], v[82:85]
	v_mfma_f32_16x16x32_bf16 v[98:101], v[162:165], v[186:189], v[98:101]
	v_mfma_f32_16x16x32_bf16 v[98:101], v[158:161], v[182:185], v[98:101]
	v_mfma_f32_16x16x32_bf16 v[114:117], v[158:161], v[174:177], v[114:117]
	v_mfma_f32_16x16x32_bf16 v[114:117], v[162:165], v[178:181], v[114:117]
	v_mfma_f32_16x16x32_bf16 v[130:133], v[162:165], v[170:173], v[130:133]
	v_mfma_f32_16x16x32_bf16 v[130:133], v[158:161], v[166:169], v[130:133]
	s_barrier
	s_setprio 0
	s_add_u32 s16, s20, 0x40000
	s_addc_u32 s17, s21, 0
	s_add_i32 s31, s31, s23
	v_lshl_add_u64 v[206:207], s[16:17], 0, v[194:195]
	s_mov_b32 m0, s31
	s_nop 0
	global_load_lds_dwordx4 v[206:207], off
	s_add_i32 m0, s31, 0x2000
	v_lshl_add_u64 v[206:207], s[16:17], 0, v[42:43]
	s_add_u32 s16, s20, 0x44000
	s_addc_u32 s17, s21, 0
	s_add_i32 s20, s42, s23
	global_load_lds_dwordx4 v[206:207], off
	v_lshl_add_u64 v[206:207], s[16:17], 0, v[194:195]
	s_mov_b32 m0, s20
	s_nop 0
	global_load_lds_dwordx4 v[206:207], off
	v_lshl_add_u64 v[206:207], s[16:17], 0, v[42:43]
	s_add_i32 m0, s20, 0x2000
	s_nop 0
	global_load_lds_dwordx4 v[206:207], off
	v_lshl_add_u64 v[206:207], s[18:19], 0, v[194:195]
	s_mov_b32 m0, s28
	s_nop 0
	global_load_lds_dwordx4 v[206:207], off
	v_lshl_add_u64 v[206:207], s[18:19], 0, v[42:43]
	s_mov_b32 m0, s29
	s_nop 0
	global_load_lds_dwordx4 v[206:207], off
	ds_read_b128 v[166:169], v45 offset:49152
	ds_read_b128 v[170:173], v45 offset:50176
	ds_read_b128 v[174:177], v45 offset:51200
	ds_read_b128 v[178:181], v45 offset:52224
	ds_read_b128 v[182:185], v45 offset:53248
	ds_read_b128 v[186:189], v45 offset:54272
	ds_read_b128 v[190:193], v45 offset:55296
	ds_read_b128 v[202:205], v45 offset:56320


	s_waitcnt vmcnt(8)
	s_waitcnt lgkmcnt(0)
	s_setprio 1
	s_barrier
	v_mfma_f32_16x16x32_bf16 v[78:81], v[62:65], v[166:169], v[78:81]
	v_mfma_f32_16x16x32_bf16 v[78:81], v[66:69], v[170:173], v[78:81]
	v_mfma_f32_16x16x32_bf16 v[54:57], v[66:69], v[178:181], v[54:57]
	v_mfma_f32_16x16x32_bf16 v[54:57], v[62:65], v[174:177], v[54:57]
	v_mfma_f32_16x16x32_bf16 v[30:33], v[62:65], v[182:185], v[30:33]
	v_mfma_f32_16x16x32_bf16 v[30:33], v[66:69], v[186:189], v[30:33]
	v_mfma_f32_16x16x32_bf16 v[14:17], v[66:69], v[202:205], v[14:17]
	v_mfma_f32_16x16x32_bf16 v[14:17], v[62:65], v[190:193], v[14:17]
	v_mfma_f32_16x16x32_bf16 v[10:13], v[70:73], v[190:193], v[10:13]
	v_mfma_f32_16x16x32_bf16 v[10:13], v[146:149], v[202:205], v[10:13]
	v_mfma_f32_16x16x32_bf16 v[26:29], v[146:149], v[186:189], v[26:29]
	v_mfma_f32_16x16x32_bf16 v[26:29], v[70:73], v[182:185], v[26:29]
	v_mfma_f32_16x16x32_bf16 v[50:53], v[70:73], v[174:177], v[50:53]
	v_mfma_f32_16x16x32_bf16 v[50:53], v[146:149], v[178:181], v[50:53]
	v_mfma_f32_16x16x32_bf16 v[74:77], v[146:149], v[170:173], v[74:77]
	v_mfma_f32_16x16x32_bf16 v[74:77], v[70:73], v[166:169], v[74:77]
	v_mfma_f32_16x16x32_bf16 v[46:49], v[150:153], v[166:169], v[46:49]
	v_mfma_f32_16x16x32_bf16 v[70:73], v[154:157], v[170:173], v[46:49]
	v_mfma_f32_16x16x32_bf16 v[46:49], v[158:161], v[166:169], v[58:61]
	v_mfma_f32_16x16x32_bf16 v[38:41], v[150:153], v[174:177], v[38:41]
	v_mfma_f32_16x16x32_bf16 v[34:37], v[158:161], v[174:177], v[34:37]
	v_mfma_f32_16x16x32_bf16 v[22:25], v[150:153], v[182:185], v[22:25]
	v_mfma_f32_16x16x32_bf16 v[18:21], v[158:161], v[182:185], v[18:21]
	v_mfma_f32_16x16x32_bf16 v[6:9], v[150:153], v[190:193], v[6:9]
	v_mfma_f32_16x16x32_bf16 v[2:5], v[158:161], v[190:193], v[2:5]
	v_mfma_f32_16x16x32_bf16 v[66:69], v[162:165], v[170:173], v[46:49]
	v_mfma_f32_16x16x32_bf16 v[38:41], v[154:157], v[178:181], v[38:41]
	v_mfma_f32_16x16x32_bf16 v[34:37], v[162:165], v[178:181], v[34:37]
	v_mfma_f32_16x16x32_bf16 v[22:25], v[154:157], v[186:189], v[22:25]
	v_mfma_f32_16x16x32_bf16 v[18:21], v[162:165], v[186:189], v[18:21]
	v_mfma_f32_16x16x32_bf16 v[6:9], v[154:157], v[202:205], v[6:9]
	v_mfma_f32_16x16x32_bf16 v[2:5], v[162:165], v[202:205], v[2:5]
	s_barrier
	s_setprio 0
	s_cmp_gt_u32 s30, 61
	s_mov_b32 s30, s4
	s_cbranch_scc1 .LBB0_1349

.LBB0_1502:
	s_or_b32 s82, s81, 1
	s_add_u32 vcc_lo, s26, vcc_lo
	s_addc_u32 vcc_hi, s27, vcc_hi
	s_and_b64 s[46:47], exec, s[46:47]
	s_cselect_b32 vcc_hi, s19, vcc_hi
	s_cselect_b32 vcc_lo, s21, vcc_lo
	s_add_u32 s46, s44, 0x280000
	s_addc_u32 s47, s45, 0
	s_add_i32 s88, 0, 0x10000
	s_add_i32 s89, 0, 0x14000
	s_mul_hi_u32 s83, s82, 0x280000
	s_mul_i32 s82, s82, 0x280000
	s_add_u32 s82, s79, s82
	s_addc_u32 s83, s80, s83
	v_lshl_add_u64 v[206:207], s[82:83], 0, v[194:195]
	s_add_i32 m0, s68, 0xc000
	s_nop 0
	global_load_lds_dwordx4 v[206:207], off
	v_lshl_add_u64 v[206:207], s[82:83], 0, v[154:155]
	s_add_i32 m0, s68, 0xe000
	s_nop 0
	global_load_lds_dwordx4 v[206:207], off
	v_add_u32_e32 v62, s88, v184
	v_add_u32_e32 v160, s89, v184
	ds_read_b128 v[50:53], v62
	ds_read_b128 v[54:57], v62 offset:1024
	ds_read_b128 v[58:61], v62 offset:2048
	ds_read_b128 v[62:65], v62 offset:3072
	ds_read_b128 v[146:149], v160
	ds_read_b128 v[150:153], v160 offset:1024
	ds_read_b128 v[156:159], v160 offset:2048
	ds_read_b128 v[160:163], v160 offset:3072
	ds_read_b128 v[164:167], v185
	ds_read_b128 v[168:171], v185 offset:1024
	ds_read_b128 v[172:175], v185 offset:2048
	ds_read_b128 v[176:179], v185 offset:3072
	ds_read_b128 v[180:183], v185 offset:4096
	ds_read_b128 v[186:189], v185 offset:5120
	ds_read_b128 v[190:193], v185 offset:6144
	ds_read_b128 v[202:205], v185 offset:7168


	s_waitcnt vmcnt(8)
	s_waitcnt lgkmcnt(0)
	s_setprio 1
	s_barrier
	v_mfma_f32_16x16x32_bf16 v[142:145], v[50:53], v[164:167], v[142:145]
	v_mfma_f32_16x16x32_bf16 v[142:145], v[54:57], v[168:171], v[142:145]
	v_mfma_f32_16x16x32_bf16 v[126:129], v[54:57], v[176:179], v[126:129]
	v_mfma_f32_16x16x32_bf16 v[126:129], v[50:53], v[172:175], v[126:129]
	v_mfma_f32_16x16x32_bf16 v[110:113], v[50:53], v[180:183], v[110:113]
	v_mfma_f32_16x16x32_bf16 v[110:113], v[54:57], v[186:189], v[110:113]
	v_mfma_f32_16x16x32_bf16 v[94:97], v[54:57], v[202:205], v[94:97]
	v_mfma_f32_16x16x32_bf16 v[94:97], v[50:53], v[190:193], v[94:97]
	v_mfma_f32_16x16x32_bf16 v[90:93], v[58:61], v[190:193], v[90:93]
	v_mfma_f32_16x16x32_bf16 v[90:93], v[62:65], v[202:205], v[90:93]
	v_mfma_f32_16x16x32_bf16 v[106:109], v[62:65], v[186:189], v[106:109]
	v_mfma_f32_16x16x32_bf16 v[106:109], v[58:61], v[180:183], v[106:109]
	v_mfma_f32_16x16x32_bf16 v[122:125], v[58:61], v[172:175], v[122:125]
	v_mfma_f32_16x16x32_bf16 v[122:125], v[62:65], v[176:179], v[122:125]
	v_mfma_f32_16x16x32_bf16 v[138:141], v[62:65], v[168:171], v[138:141]
	v_mfma_f32_16x16x32_bf16 v[138:141], v[58:61], v[164:167], v[138:141]
	v_mfma_f32_16x16x32_bf16 v[134:137], v[146:149], v[164:167], v[134:137]
	v_mfma_f32_16x16x32_bf16 v[134:137], v[150:153], v[168:171], v[134:137]
	v_mfma_f32_16x16x32_bf16 v[118:121], v[150:153], v[176:179], v[118:121]
	v_mfma_f32_16x16x32_bf16 v[118:121], v[146:149], v[172:175], v[118:121]
	v_mfma_f32_16x16x32_bf16 v[102:105], v[146:149], v[180:183], v[102:105]
	v_mfma_f32_16x16x32_bf16 v[102:105], v[150:153], v[186:189], v[102:105]
	v_mfma_f32_16x16x32_bf16 v[86:89], v[150:153], v[202:205], v[86:89]
	v_mfma_f32_16x16x32_bf16 v[86:89], v[146:149], v[190:193], v[86:89]
	v_mfma_f32_16x16x32_bf16 v[82:85], v[156:159], v[190:193], v[82:85]
	v_mfma_f32_16x16x32_bf16 v[82:85], v[160:163], v[202:205], v[82:85]
	v_mfma_f32_16x16x32_bf16 v[98:101], v[160:163], v[186:189], v[98:101]
	v_mfma_f32_16x16x32_bf16 v[98:101], v[156:159], v[180:183], v[98:101]
	v_mfma_f32_16x16x32_bf16 v[114:117], v[156:159], v[172:175], v[114:117]
	v_mfma_f32_16x16x32_bf16 v[114:117], v[160:163], v[176:179], v[114:117]
	v_mfma_f32_16x16x32_bf16 v[130:133], v[160:163], v[168:171], v[130:133]
	v_mfma_f32_16x16x32_bf16 v[130:133], v[156:159], v[164:167], v[130:133]
	s_barrier
	s_setprio 0
	s_add_i32 s82, s88, s67
	v_lshl_add_u64 v[206:207], vcc, 0, v[194:195]
	s_mov_b32 m0, s82
	s_nop 0
	global_load_lds_dwordx4 v[206:207], off
	s_add_i32 m0, s82, 0x2000
	s_add_u32 s82, vcc_lo, 0x4000
	v_lshl_add_u64 v[206:207], vcc, 0, v[154:155]
	s_addc_u32 s83, vcc_hi, 0
	s_add_i32 s88, s89, s67
	global_load_lds_dwordx4 v[206:207], off
	v_lshl_add_u64 v[206:207], s[82:83], 0, v[194:195]
	s_mov_b32 m0, s88
	s_nop 0
	global_load_lds_dwordx4 v[206:207], off
	v_lshl_add_u64 v[206:207], s[82:83], 0, v[154:155]
	s_add_i32 m0, s88, 0x2000
	s_nop 0
	global_load_lds_dwordx4 v[206:207], off
	v_lshl_add_u64 v[206:207], s[44:45], 0, v[194:195]
	s_mov_b32 m0, s68
	s_nop 0
	global_load_lds_dwordx4 v[206:207], off
	v_lshl_add_u64 v[206:207], s[44:45], 0, v[154:155]
	s_mov_b32 m0, s69
	s_nop 0
	global_load_lds_dwordx4 v[206:207], off
	ds_read_b128 v[164:167], v185 offset:16384
	ds_read_b128 v[168:171], v185 offset:17408
	ds_read_b128 v[172:175], v185 offset:18432
	ds_read_b128 v[176:179], v185 offset:19456
	ds_read_b128 v[180:183], v185 offset:20480
	ds_read_b128 v[186:189], v185 offset:21504
	ds_read_b128 v[190:193], v185 offset:22528
	ds_read_b128 v[202:205], v185 offset:23552


	s_waitcnt vmcnt(8)
	s_waitcnt lgkmcnt(0)
	s_setprio 1
	s_barrier
	v_mfma_f32_16x16x32_bf16 v[78:81], v[50:53], v[164:167], v[78:81]
	v_mfma_f32_16x16x32_bf16 v[78:81], v[54:57], v[168:171], v[78:81]
	v_mfma_f32_16x16x32_bf16 v[46:49], v[54:57], v[176:179], v[46:49]
	v_mfma_f32_16x16x32_bf16 v[46:49], v[50:53], v[172:175], v[46:49]
	v_mfma_f32_16x16x32_bf16 v[30:33], v[50:53], v[180:183], v[30:33]
	v_mfma_f32_16x16x32_bf16 v[30:33], v[54:57], v[186:189], v[30:33]
	v_mfma_f32_16x16x32_bf16 v[14:17], v[54:57], v[202:205], v[14:17]
	v_mfma_f32_16x16x32_bf16 v[14:17], v[50:53], v[190:193], v[14:17]
	v_mfma_f32_16x16x32_bf16 v[10:13], v[58:61], v[190:193], v[10:13]
	v_mfma_f32_16x16x32_bf16 v[10:13], v[62:65], v[202:205], v[10:13]
	v_mfma_f32_16x16x32_bf16 v[26:29], v[62:65], v[186:189], v[26:29]
	v_mfma_f32_16x16x32_bf16 v[26:29], v[58:61], v[180:183], v[26:29]
	v_mfma_f32_16x16x32_bf16 v[42:45], v[58:61], v[172:175], v[42:45]
	v_mfma_f32_16x16x32_bf16 v[42:45], v[62:65], v[176:179], v[42:45]
	v_mfma_f32_16x16x32_bf16 v[74:77], v[62:65], v[168:171], v[74:77]
	v_mfma_f32_16x16x32_bf16 v[74:77], v[58:61], v[164:167], v[74:77]
	v_mfma_f32_16x16x32_bf16 v[38:41], v[146:149], v[172:175], v[38:41]
	v_mfma_f32_16x16x32_bf16 v[34:37], v[156:159], v[172:175], v[34:37]
	v_mfma_f32_16x16x32_bf16 v[22:25], v[146:149], v[180:183], v[22:25]
	v_mfma_f32_16x16x32_bf16 v[18:21], v[156:159], v[180:183], v[18:21]
	v_mfma_f32_16x16x32_bf16 v[6:9], v[146:149], v[190:193], v[6:9]
	v_mfma_f32_16x16x32_bf16 v[2:5], v[156:159], v[190:193], v[2:5]
	v_mfma_f32_16x16x32_bf16 v[50:53], v[146:149], v[164:167], v[70:73]
	v_mfma_f32_16x16x32_bf16 v[54:57], v[156:159], v[164:167], v[66:69]
	v_mfma_f32_16x16x32_bf16 v[38:41], v[150:153], v[176:179], v[38:41]
	v_mfma_f32_16x16x32_bf16 v[34:37], v[160:163], v[176:179], v[34:37]
	v_mfma_f32_16x16x32_bf16 v[22:25], v[150:153], v[186:189], v[22:25]
	v_mfma_f32_16x16x32_bf16 v[18:21], v[160:163], v[186:189], v[18:21]
	v_mfma_f32_16x16x32_bf16 v[6:9], v[150:153], v[202:205], v[6:9]
	v_mfma_f32_16x16x32_bf16 v[2:5], v[160:163], v[202:205], v[2:5]
	v_mfma_f32_16x16x32_bf16 v[50:53], v[150:153], v[168:171], v[50:53]
	v_mfma_f32_16x16x32_bf16 v[54:57], v[160:163], v[168:171], v[54:57]
	s_barrier
	s_setprio 0
	s_add_i32 s82, 0, 0x18000
	s_add_i32 s83, 0, 0x1c000
	s_add_u32 s44, s44, 0x4000
	s_addc_u32 s45, s45, 0
	s_mov_b32 m0, s72
	v_lshl_add_u64 v[206:207], s[44:45], 0, v[194:195]
	global_load_lds_dwordx4 v[206:207], off
	v_lshl_add_u64 v[206:207], s[44:45], 0, v[154:155]
	s_mov_b32 m0, s73
	s_nop 0
	global_load_lds_dwordx4 v[206:207], off
	v_add_u32_e32 v70, s82, v184
	v_add_u32_e32 v160, s83, v184
	ds_read_b128 v[58:61], v70
	ds_read_b128 v[62:65], v70 offset:1024
	ds_read_b128 v[66:69], v70 offset:2048
	ds_read_b128 v[70:73], v70 offset:3072
	ds_read_b128 v[146:149], v160
	ds_read_b128 v[150:153], v160 offset:1024
	ds_read_b128 v[156:159], v160 offset:2048
	ds_read_b128 v[160:163], v160 offset:3072
	ds_read_b128 v[164:167], v185 offset:32768
	ds_read_b128 v[168:171], v185 offset:33792
	ds_read_b128 v[172:175], v185 offset:34816
	ds_read_b128 v[176:179], v185 offset:35840
	ds_read_b128 v[180:183], v185 offset:36864
	ds_read_b128 v[186:189], v185 offset:37888
	ds_read_b128 v[190:193], v185 offset:38912
	ds_read_b128 v[202:205], v185 offset:39936


	s_waitcnt vmcnt(8)
	s_waitcnt lgkmcnt(0)
	s_setprio 1
	s_barrier
	v_mfma_f32_16x16x32_bf16 v[142:145], v[58:61], v[164:167], v[142:145]
	v_mfma_f32_16x16x32_bf16 v[142:145], v[62:65], v[168:171], v[142:145]
	v_mfma_f32_16x16x32_bf16 v[126:129], v[62:65], v[176:179], v[126:129]
	v_mfma_f32_16x16x32_bf16 v[126:129], v[58:61], v[172:175], v[126:129]
	v_mfma_f32_16x16x32_bf16 v[110:113], v[58:61], v[180:183], v[110:113]
	v_mfma_f32_16x16x32_bf16 v[110:113], v[62:65], v[186:189], v[110:113]
	v_mfma_f32_16x16x32_bf16 v[94:97], v[62:65], v[202:205], v[94:97]
	v_mfma_f32_16x16x32_bf16 v[94:97], v[58:61], v[190:193], v[94:97]
	v_mfma_f32_16x16x32_bf16 v[90:93], v[66:69], v[190:193], v[90:93]
	v_mfma_f32_16x16x32_bf16 v[90:93], v[70:73], v[202:205], v[90:93]
	v_mfma_f32_16x16x32_bf16 v[106:109], v[70:73], v[186:189], v[106:109]
	v_mfma_f32_16x16x32_bf16 v[106:109], v[66:69], v[180:183], v[106:109]
	v_mfma_f32_16x16x32_bf16 v[122:125], v[66:69], v[172:175], v[122:125]
	v_mfma_f32_16x16x32_bf16 v[122:125], v[70:73], v[176:179], v[122:125]
	v_mfma_f32_16x16x32_bf16 v[138:141], v[70:73], v[168:171], v[138:141]
	v_mfma_f32_16x16x32_bf16 v[138:141], v[66:69], v[164:167], v[138:141]
	v_mfma_f32_16x16x32_bf16 v[134:137], v[146:149], v[164:167], v[134:137]
	v_mfma_f32_16x16x32_bf16 v[134:137], v[150:153], v[168:171], v[134:137]
	v_mfma_f32_16x16x32_bf16 v[118:121], v[150:153], v[176:179], v[118:121]
	v_mfma_f32_16x16x32_bf16 v[118:121], v[146:149], v[172:175], v[118:121]
	v_mfma_f32_16x16x32_bf16 v[102:105], v[146:149], v[180:183], v[102:105]
	v_mfma_f32_16x16x32_bf16 v[102:105], v[150:153], v[186:189], v[102:105]
	v_mfma_f32_16x16x32_bf16 v[86:89], v[150:153], v[202:205], v[86:89]
	v_mfma_f32_16x16x32_bf16 v[86:89], v[146:149], v[190:193], v[86:89]
	v_mfma_f32_16x16x32_bf16 v[82:85], v[156:159], v[190:193], v[82:85]
	v_mfma_f32_16x16x32_bf16 v[82:85], v[160:163], v[202:205], v[82:85]
	v_mfma_f32_16x16x32_bf16 v[98:101], v[160:163], v[186:189], v[98:101]
	v_mfma_f32_16x16x32_bf16 v[98:101], v[156:159], v[180:183], v[98:101]
	v_mfma_f32_16x16x32_bf16 v[114:117], v[156:159], v[172:175], v[114:117]
	v_mfma_f32_16x16x32_bf16 v[114:117], v[160:163], v[176:179], v[114:117]
	v_mfma_f32_16x16x32_bf16 v[130:133], v[160:163], v[168:171], v[130:133]
	v_mfma_f32_16x16x32_bf16 v[130:133], v[156:159], v[164:167], v[130:133]
	s_barrier
	s_setprio 0
	s_add_u32 s44, vcc_lo, 0x40000
	s_addc_u32 s45, vcc_hi, 0
	s_add_i32 s82, s82, s67
	v_lshl_add_u64 v[206:207], s[44:45], 0, v[194:195]
	s_mov_b32 m0, s82
	s_nop 0
	global_load_lds_dwordx4 v[206:207], off
	s_add_i32 m0, s82, 0x2000
	v_lshl_add_u64 v[206:207], s[44:45], 0, v[154:155]
	s_add_u32 s44, vcc_lo, 0x44000
	s_addc_u32 s45, vcc_hi, 0
	s_add_i32 s82, s83, s67
	global_load_lds_dwordx4 v[206:207], off
	v_lshl_add_u64 v[206:207], s[44:45], 0, v[194:195]
	s_mov_b32 m0, s82
	s_nop 0
	global_load_lds_dwordx4 v[206:207], off
	v_lshl_add_u64 v[206:207], s[44:45], 0, v[154:155]
	s_add_i32 m0, s82, 0x2000
	s_nop 0
	global_load_lds_dwordx4 v[206:207], off
	v_lshl_add_u64 v[206:207], s[46:47], 0, v[194:195]
	s_mov_b32 m0, s76
	s_nop 0
	global_load_lds_dwordx4 v[206:207], off
	v_lshl_add_u64 v[206:207], s[46:47], 0, v[154:155]
	s_mov_b32 m0, s77
	s_nop 0
	global_load_lds_dwordx4 v[206:207], off
	ds_read_b128 v[164:167], v185 offset:49152
	ds_read_b128 v[168:171], v185 offset:50176
	ds_read_b128 v[172:175], v185 offset:51200
	ds_read_b128 v[176:179], v185 offset:52224
	ds_read_b128 v[180:183], v185 offset:53248
	ds_read_b128 v[186:189], v185 offset:54272
	ds_read_b128 v[190:193], v185 offset:55296
	ds_read_b128 v[202:205], v185 offset:56320


	s_waitcnt vmcnt(8)
	s_waitcnt lgkmcnt(0)
	s_setprio 1
	s_barrier
	v_mfma_f32_16x16x32_bf16 v[78:81], v[58:61], v[164:167], v[78:81]
	v_mfma_f32_16x16x32_bf16 v[78:81], v[62:65], v[168:171], v[78:81]
	v_mfma_f32_16x16x32_bf16 v[46:49], v[62:65], v[176:179], v[46:49]
	v_mfma_f32_16x16x32_bf16 v[46:49], v[58:61], v[172:175], v[46:49]
	v_mfma_f32_16x16x32_bf16 v[30:33], v[58:61], v[180:183], v[30:33]
	v_mfma_f32_16x16x32_bf16 v[30:33], v[62:65], v[186:189], v[30:33]
	v_mfma_f32_16x16x32_bf16 v[14:17], v[62:65], v[202:205], v[14:17]
	v_mfma_f32_16x16x32_bf16 v[14:17], v[58:61], v[190:193], v[14:17]
	v_mfma_f32_16x16x32_bf16 v[10:13], v[66:69], v[190:193], v[10:13]
	v_mfma_f32_16x16x32_bf16 v[10:13], v[70:73], v[202:205], v[10:13]
	v_mfma_f32_16x16x32_bf16 v[26:29], v[70:73], v[186:189], v[26:29]
	v_mfma_f32_16x16x32_bf16 v[26:29], v[66:69], v[180:183], v[26:29]
	v_mfma_f32_16x16x32_bf16 v[42:45], v[66:69], v[172:175], v[42:45]
	v_mfma_f32_16x16x32_bf16 v[42:45], v[70:73], v[176:179], v[42:45]
	v_mfma_f32_16x16x32_bf16 v[74:77], v[70:73], v[168:171], v[74:77]
	v_mfma_f32_16x16x32_bf16 v[74:77], v[66:69], v[164:167], v[74:77]
	v_mfma_f32_16x16x32_bf16 v[50:53], v[146:149], v[164:167], v[50:53]
	v_mfma_f32_16x16x32_bf16 v[70:73], v[150:153], v[168:171], v[50:53]
	v_mfma_f32_16x16x32_bf16 v[50:53], v[156:159], v[164:167], v[54:57]
	v_mfma_f32_16x16x32_bf16 v[38:41], v[146:149], v[172:175], v[38:41]
	v_mfma_f32_16x16x32_bf16 v[34:37], v[156:159], v[172:175], v[34:37]
	v_mfma_f32_16x16x32_bf16 v[22:25], v[146:149], v[180:183], v[22:25]
	v_mfma_f32_16x16x32_bf16 v[18:21], v[156:159], v[180:183], v[18:21]
	v_mfma_f32_16x16x32_bf16 v[6:9], v[146:149], v[190:193], v[6:9]
	v_mfma_f32_16x16x32_bf16 v[2:5], v[156:159], v[190:193], v[2:5]
	v_mfma_f32_16x16x32_bf16 v[66:69], v[160:163], v[168:171], v[50:53]
	v_mfma_f32_16x16x32_bf16 v[38:41], v[150:153], v[176:179], v[38:41]
	v_mfma_f32_16x16x32_bf16 v[34:37], v[160:163], v[176:179], v[34:37]
	v_mfma_f32_16x16x32_bf16 v[22:25], v[150:153], v[186:189], v[22:25]
	v_mfma_f32_16x16x32_bf16 v[18:21], v[160:163], v[186:189], v[18:21]
	v_mfma_f32_16x16x32_bf16 v[6:9], v[150:153], v[202:205], v[6:9]
	v_mfma_f32_16x16x32_bf16 v[2:5], v[160:163], v[202:205], v[2:5]
	s_barrier
	s_setprio 0
	s_cmpk_gt_u32 s81, 0x7d
	s_mov_b32 s81, s4
	s_cbranch_scc1 .LBB0_1505
